# GEMM loops (gate/up x2, w_in): LDS-DMA issued with SGPR base + 32-bit VGPR offset, 64-bit VALU address adds removed
# speedup vs baseline: 1.0053x; 1.0053x over previous
;     __device__ bool next(int i, Unit& u) const { if (!so.next(i >> 1, u)) return false; u.kind = i & 1; return true; }
; #define PG8_STAGE(bufoff, gbase, voff) do { _Pragma("unroll") for (int _i = 0; _i < 2; ++_i) \
;         __builtin_amdgcn_global_load_lds((const unsigned*)((const char*)(gbase) + (voff)[_i]), (LAS unsigned*)(lds + (bufoff) + ldsw + _i * 8192), 16, 0, 0); } while (0)
; #define PG8_LDA(dst, b, h) do { _Pragma("unroll") for (int m = 0; m < 4; ++m) _Pragma("unroll") for (int k = 0; k < 2; ++k) dst[m][k] = *(const LAS bf16x8*)(lds + PG8_SA(b, h) + aoff + m * 2048 + k * 1024); } while (0)
; #define PG8_LDB(dst, b, h) do { _Pragma("unroll") for (int n = 0; n < 2; ++n) _Pragma("unroll") for (int k = 0; k < 2; ++k) dst[n][k] = *(const LAS bf16x8*)(lds + PG8_SB(b, h) + boff + n * 2048 + k * 1024); } while (0)
; #define PG8_WAIT_V(n) asm volatile("s_waitcnt vmcnt(" #n ")" ::: "memory")
; #define PG8_WAIT_L(n) asm volatile("s_waitcnt lgkmcnt(" #n ")" ::: "memory")
; #define PG8_BAR __builtin_amdgcn_s_barrier()
; template <class Epi, class Sched, bool ALIGN_EPI = true, bool SP2 = true>
; __device__ __forceinline__ void gemm_phase(LAS unsigned char* lds, const Gemm g, const Sched& S, const Epi& E) {
;     ...
;         const bool has_next = S.next(ui + 1, nxt);
;         const char* nA = has_next ? (const char*)(nxt.kind ? g.A1 : g.A0) + (size_t)nxt.pm * tstep : cA; const char* nB = has_next ? (const char*)(nxt.kind ? g.B1 : g.B0) + (size_t)nxt.pn * tstep : cB;
;         for (int t = 0; t < nt; t += 2) {
;             const bool last = (t == nt - 2);
;             const char* a1 = cA + (size_t)(t + 1) * kstep;
;             const char* a2 = last ? nA : cA + (size_t)(t + 2) * kstep; const char* b2 = last ? nB : cB + (size_t)(t + 2) * kstep;
;             const char* a3 = a2 + kstep; const char* b3 = b2 + kstep;
;             if constexpr (SP2) {
;             PG8_LDB(B0, 0, 0); PG8_LDB(B1, 0, 1); PG8_SCHED; PG8_LDA(At, 0, 0); PG8_STAGE(PG8_SA(1, 1), a1 + hstep, voffA);
;             PG8_WAIT_V(8); PG8_WAIT_L(0); PG8_BAR; PG8_MMA(0, 0, At, B0); PG8_MMA(0, 1, At, B1); PG8_BAR; PG8_SCHED;
;             PG8_LDA(At, 0, 1); PG8_STAGE(PG8_SB(0, 0), b2, voffB); PG8_STAGE(PG8_SB(0, 1), b2 + hstep, voffB); PG8_STAGE(PG8_SA(0, 0), a2, voffA);
;             PG8_WAIT_V(8); PG8_WAIT_L(0); PG8_BAR; PG8_MMA(1, 0, At, B0); PG8_MMA(1, 1, At, B1); PG8_BAR; PG8_SCHED;
.LBB0_93:
	s_ashr_i32 s17, s16, 31
	s_lshl_b64 s[18:19], s[16:17], 20
	s_add_u32 s18, s88, s18
	s_addc_u32 s19, s89, s19
	s_and_b64 s[20:21], s[0:1], exec
	s_cselect_b32 s17, s19, s7
	s_cselect_b32 s56, s18, s6
	s_ashr_i32 s15, s14, 31
	s_lshl_b64 s[20:21], s[14:15], 20
	v_readlane_b32 s15, v255, 28
	s_add_u32 s20, s15, s20
	v_readlane_b32 s15, v255, 29
	s_addc_u32 s21, s15, s21
	s_and_b64 s[22:23], s[0:1], exec
	s_cselect_b32 s15, s21, s9
	s_cselect_b32 s57, s20, s8
	s_add_u32 s6, s6, 0x80080
	s_addc_u32 s7, s7, 0
	s_add_u32 s70, s8, 0x100
	s_addc_u32 s71, s9, 0
	s_mov_b32 s72, -2
	s_add_u32 s8, s6, 0xfff80080
	s_addc_u32 s9, s7, -1
	s_add_i32 s58, 0, 0x10000
	s_cmp_eq_u32 s72, 28
	s_cselect_b32 s23, s17, s9
	s_cselect_b32 s22, s56, s8
	v_add_u32_e32 v148, s58, v153
	s_cselect_b32 s9, s15, s71
	s_cselect_b32 s8, s57, s70
	s_add_i32 s73, 0, 0x14000
	ds_read_b128 v[140:143], v148
	ds_read_b128 v[144:147], v148 offset:1024
	ds_read_b128 v[160:163], v148 offset:2048
	ds_read_b128 v[164:167], v148 offset:3072
	ds_read_b128 v[168:171], v148 offset:16384
	ds_read_b128 v[172:175], v148 offset:17408
	ds_read_b128 v[176:179], v148 offset:18432
	ds_read_b128 v[194:197], v148 offset:19456
	s_add_i32 m0, s25, 0xc000
	ds_read_b128 v[198:201], v159
	ds_read_b128 v[202:205], v159 offset:1024
	ds_read_b128 v[206:209], v159 offset:2048
	ds_read_b128 v[210:213], v159 offset:3072
	ds_read_b128 v[234:237], v159 offset:4096
	ds_read_b128 v[238:241], v159 offset:5120
	ds_read_b128 v[242:245], v159 offset:6144
	ds_read_b128 v[246:249], v159 offset:7168
	global_load_lds_dwordx4 v136, s[6:7]
	s_add_i32 m0, s25, 0xe000
	s_nop 0
	global_load_lds_dwordx4 v138, s[6:7]
	s_waitcnt vmcnt(8)
	s_waitcnt lgkmcnt(0)
	s_barrier
	s_setprio 1
	s_waitcnt lgkmcnt(0)
	v_mfma_f32_16x16x32_bf16 v[126:129], v[140:143], v[198:201], 0
	v_mfma_f32_16x16x32_bf16 v[118:121], v[160:163], v[198:201], 0
	v_mfma_f32_16x16x32_bf16 v[110:113], v[140:143], v[206:209], 0
	v_mfma_f32_16x16x32_bf16 v[102:105], v[160:163], v[206:209], 0
	v_mfma_f32_16x16x32_bf16 v[94:97], v[140:143], v[234:237], 0
	v_mfma_f32_16x16x32_bf16 v[86:89], v[160:163], v[234:237], 0
	v_mfma_f32_16x16x32_bf16 v[78:81], v[140:143], v[242:245], 0
	v_mfma_f32_16x16x32_bf16 v[70:73], v[160:163], v[242:245], 0
	v_mfma_f32_16x16x32_bf16 v[126:129], v[144:147], v[202:205], v[126:129]
	v_mfma_f32_16x16x32_bf16 v[118:121], v[164:167], v[202:205], v[118:121]
	v_mfma_f32_16x16x32_bf16 v[110:113], v[144:147], v[210:213], v[110:113]
	v_mfma_f32_16x16x32_bf16 v[102:105], v[164:167], v[210:213], v[102:105]
	v_mfma_f32_16x16x32_bf16 v[94:97], v[144:147], v[238:241], v[94:97]
	v_mfma_f32_16x16x32_bf16 v[86:89], v[164:167], v[238:241], v[86:89]
	v_mfma_f32_16x16x32_bf16 v[78:81], v[144:147], v[246:249], v[78:81]
	v_mfma_f32_16x16x32_bf16 v[70:73], v[164:167], v[246:249], v[70:73]
	s_setprio 0
	s_setprio 1
	v_mfma_f32_16x16x32_bf16 v[122:125], v[168:171], v[198:201], 0
	v_mfma_f32_16x16x32_bf16 v[114:117], v[176:179], v[198:201], 0
	v_mfma_f32_16x16x32_bf16 v[106:109], v[168:171], v[206:209], 0
	v_mfma_f32_16x16x32_bf16 v[98:101], v[176:179], v[206:209], 0
	v_mfma_f32_16x16x32_bf16 v[90:93], v[168:171], v[234:237], 0
	v_mfma_f32_16x16x32_bf16 v[82:85], v[176:179], v[234:237], 0
	v_mfma_f32_16x16x32_bf16 v[74:77], v[168:171], v[242:245], 0
	v_mfma_f32_16x16x32_bf16 v[66:69], v[176:179], v[242:245], 0
	v_mfma_f32_16x16x32_bf16 v[122:125], v[172:175], v[202:205], v[122:125]
	v_mfma_f32_16x16x32_bf16 v[114:117], v[194:197], v[202:205], v[114:117]
	v_mfma_f32_16x16x32_bf16 v[106:109], v[172:175], v[210:213], v[106:109]
	v_mfma_f32_16x16x32_bf16 v[98:101], v[194:197], v[210:213], v[98:101]
	v_mfma_f32_16x16x32_bf16 v[90:93], v[172:175], v[238:241], v[90:93]
	v_mfma_f32_16x16x32_bf16 v[82:85], v[194:197], v[238:241], v[82:85]
	v_mfma_f32_16x16x32_bf16 v[74:77], v[172:175], v[246:249], v[74:77]
	v_mfma_f32_16x16x32_bf16 v[66:69], v[194:197], v[246:249], v[66:69]
	s_setprio 0
	s_barrier
	s_add_i32 s58, s58, s24
	s_mov_b32 m0, s58
	ds_read_b128 v[198:201], v159 offset:16384
	ds_read_b128 v[202:205], v159 offset:17408
	ds_read_b128 v[206:209], v159 offset:18432
	ds_read_b128 v[210:213], v159 offset:19456
	ds_read_b128 v[234:237], v159 offset:20480
	ds_read_b128 v[238:241], v159 offset:21504
	ds_read_b128 v[242:245], v159 offset:22528
	ds_read_b128 v[246:249], v159 offset:23552
	global_load_lds_dwordx4 v0, s[8:9]
	s_add_i32 m0, s58, 0x2000
	s_add_u32 s58, s8, 0x80000
	s_addc_u32 s59, s9, 0
	s_add_i32 s73, s73, s24
	global_load_lds_dwordx4 v130, s[8:9]
	s_mov_b32 m0, s73
	s_nop 0
	global_load_lds_dwordx4 v0, s[58:59]
	s_add_i32 m0, s73, 0x2000
	s_nop 0
	global_load_lds_dwordx4 v130, s[58:59]
	s_mov_b32 m0, s25
	s_nop 0
	global_load_lds_dwordx4 v134, s[22:23]
	s_mov_b32 m0, s26
	s_nop 0
	global_load_lds_dwordx4 v132, s[22:23]
	s_waitcnt vmcnt(8)
	s_waitcnt lgkmcnt(0)
	s_barrier
; #define PG8_STAGE(bufoff, gbase, voff) do { _Pragma("unroll") for (int _i = 0; _i < 2; ++_i) \
;         __builtin_amdgcn_global_load_lds((const unsigned*)((const char*)(gbase) + (voff)[_i]), (LAS unsigned*)(lds + (bufoff) + ldsw + _i * 8192), 16, 0, 0); } while (0)
; #define PG8_LDA(dst, b, h) do { _Pragma("unroll") for (int m = 0; m < 4; ++m) _Pragma("unroll") for (int k = 0; k < 2; ++k) dst[m][k] = *(const LAS bf16x8*)(lds + PG8_SA(b, h) + aoff + m * 2048 + k * 1024); } while (0)
; #define PG8_LDB(dst, b, h) do { _Pragma("unroll") for (int n = 0; n < 2; ++n) _Pragma("unroll") for (int k = 0; k < 2; ++k) dst[n][k] = *(const LAS bf16x8*)(lds + PG8_SB(b, h) + boff + n * 2048 + k * 1024); } while (0)
; #define PG8_MMA(ai, bj, At, Bt) do { __builtin_amdgcn_s_setprio(1); _Pragma("unroll") for (int m = 0; m < 4; ++m) _Pragma("unroll") for (int n = 0; n < 2; ++n) _Pragma("unroll") for (int k = 0; k < 2; ++k) \
;         acc[ai][bj][m][n] = __builtin_amdgcn_mfma_f32_16x16x32_bf16(Bt[n][k], At[m][k], acc[ai][bj][m][n], 0, 0, 0); __builtin_amdgcn_s_setprio(0); } while (0)
; #define PG8_WAIT_V(n) asm volatile("s_waitcnt vmcnt(" #n ")" ::: "memory")
; #define PG8_WAIT_L(n) asm volatile("s_waitcnt lgkmcnt(" #n ")" ::: "memory")
; #define PG8_BAR __builtin_amdgcn_s_barrier()
; #define PG8_SCHED __builtin_amdgcn_sched_barrier(0)
; template <class Epi, class Sched, bool ALIGN_EPI = true, bool SP2 = true>
; __device__ __forceinline__ void gemm_phase(LAS unsigned char* lds, const Gemm g, const Sched& S, const Epi& E) {
;     ...
;             PG8_WAIT_V(8); PG8_WAIT_L(0); PG8_BAR; PG8_MMA(1, 0, At, B0); PG8_MMA(1, 1, At, B1); PG8_BAR; PG8_SCHED;
;             PG8_LDB(B0, 1, 0); PG8_LDB(B1, 1, 1); PG8_SCHED; PG8_LDA(At, 1, 0); PG8_STAGE(PG8_SA(0, 1), a2 + hstep, voffA);
;             PG8_WAIT_V(8); PG8_WAIT_L(0); PG8_BAR; PG8_MMA(0, 0, At, B0); PG8_MMA(0, 1, At, B1); PG8_BAR; PG8_SCHED;
;             PG8_LDA(At, 1, 1); PG8_STAGE(PG8_SB(1, 0), b3, voffB); PG8_STAGE(PG8_SB(1, 1), b3 + hstep, voffB); PG8_STAGE(PG8_SA(1, 0), a3, voffA);
	s_setprio 1
	s_waitcnt lgkmcnt(0)
	v_mfma_f32_16x16x32_bf16 v[62:65], v[140:143], v[198:201], 0
	v_mfma_f32_16x16x32_bf16 v[54:57], v[160:163], v[198:201], 0
	v_mfma_f32_16x16x32_bf16 v[46:49], v[140:143], v[206:209], 0
	v_mfma_f32_16x16x32_bf16 v[38:41], v[160:163], v[206:209], 0
	v_mfma_f32_16x16x32_bf16 v[30:33], v[140:143], v[234:237], 0
	v_mfma_f32_16x16x32_bf16 v[22:25], v[160:163], v[234:237], 0
	v_mfma_f32_16x16x32_bf16 v[14:17], v[140:143], v[242:245], 0
	v_mfma_f32_16x16x32_bf16 v[6:9], v[160:163], v[242:245], 0
	v_mfma_f32_16x16x32_bf16 v[62:65], v[144:147], v[202:205], v[62:65]
	v_mfma_f32_16x16x32_bf16 v[54:57], v[164:167], v[202:205], v[54:57]
	v_mfma_f32_16x16x32_bf16 v[46:49], v[144:147], v[210:213], v[46:49]
	v_mfma_f32_16x16x32_bf16 v[38:41], v[164:167], v[210:213], v[38:41]
	v_mfma_f32_16x16x32_bf16 v[30:33], v[144:147], v[238:241], v[30:33]
	v_mfma_f32_16x16x32_bf16 v[22:25], v[164:167], v[238:241], v[22:25]
	v_mfma_f32_16x16x32_bf16 v[14:17], v[144:147], v[246:249], v[14:17]
	v_mfma_f32_16x16x32_bf16 v[6:9], v[164:167], v[246:249], v[6:9]
	s_setprio 0
	s_setprio 1
	v_mfma_f32_16x16x32_bf16 v[58:61], v[168:171], v[198:201], 0
	v_mfma_f32_16x16x32_bf16 v[50:53], v[176:179], v[198:201], 0
	v_mfma_f32_16x16x32_bf16 v[42:45], v[168:171], v[206:209], 0
	v_mfma_f32_16x16x32_bf16 v[34:37], v[176:179], v[206:209], 0
	v_mfma_f32_16x16x32_bf16 v[26:29], v[168:171], v[234:237], 0
	v_mfma_f32_16x16x32_bf16 v[18:21], v[176:179], v[234:237], 0
	v_mfma_f32_16x16x32_bf16 v[10:13], v[168:171], v[242:245], 0
	v_mfma_f32_16x16x32_bf16 v[2:5], v[176:179], v[242:245], 0
	v_mfma_f32_16x16x32_bf16 v[58:61], v[172:175], v[202:205], v[58:61]
	v_mfma_f32_16x16x32_bf16 v[50:53], v[194:197], v[202:205], v[50:53]
	v_mfma_f32_16x16x32_bf16 v[42:45], v[172:175], v[210:213], v[42:45]
	v_mfma_f32_16x16x32_bf16 v[34:37], v[194:197], v[210:213], v[34:37]
	v_mfma_f32_16x16x32_bf16 v[26:29], v[172:175], v[238:241], v[26:29]
	v_mfma_f32_16x16x32_bf16 v[18:21], v[194:197], v[238:241], v[18:21]
	v_mfma_f32_16x16x32_bf16 v[10:13], v[172:175], v[246:249], v[10:13]
	v_mfma_f32_16x16x32_bf16 v[2:5], v[194:197], v[246:249], v[2:5]
	s_setprio 0
	s_barrier
	s_add_i32 s58, 0, 0x18000
	v_add_u32_e32 v150, s58, v153
	s_add_i32 s59, 0, 0x1c000
	ds_read_b128 v[140:143], v150
	ds_read_b128 v[144:147], v150 offset:1024
	ds_read_b128 v[160:163], v150 offset:2048
	ds_read_b128 v[164:167], v150 offset:3072
	ds_read_b128 v[168:171], v150 offset:16384
	ds_read_b128 v[172:175], v150 offset:17408
	ds_read_b128 v[176:179], v150 offset:18432
	ds_read_b128 v[194:197], v150 offset:19456
	s_add_u32 s22, s22, 0x80000
	s_addc_u32 s23, s23, 0
	s_mov_b32 m0, s27
	ds_read_b128 v[198:201], v159 offset:32768
	ds_read_b128 v[202:205], v159 offset:33792
	ds_read_b128 v[206:209], v159 offset:34816
	ds_read_b128 v[210:213], v159 offset:35840
	ds_read_b128 v[234:237], v159 offset:36864
	ds_read_b128 v[238:241], v159 offset:37888
	ds_read_b128 v[242:245], v159 offset:38912
	ds_read_b128 v[246:249], v159 offset:39936
	global_load_lds_dwordx4 v134, s[22:23]
	s_mov_b32 m0, s28
	s_nop 0
	global_load_lds_dwordx4 v132, s[22:23]
	s_waitcnt vmcnt(8)
	s_waitcnt lgkmcnt(0)
	s_barrier
	s_setprio 1
	s_waitcnt lgkmcnt(0)
	v_mfma_f32_16x16x32_bf16 v[126:129], v[140:143], v[198:201], v[126:129]
	v_mfma_f32_16x16x32_bf16 v[118:121], v[160:163], v[198:201], v[118:121]
	v_mfma_f32_16x16x32_bf16 v[110:113], v[140:143], v[206:209], v[110:113]
	v_mfma_f32_16x16x32_bf16 v[102:105], v[160:163], v[206:209], v[102:105]
	v_mfma_f32_16x16x32_bf16 v[94:97], v[140:143], v[234:237], v[94:97]
	v_mfma_f32_16x16x32_bf16 v[86:89], v[160:163], v[234:237], v[86:89]
	v_mfma_f32_16x16x32_bf16 v[78:81], v[140:143], v[242:245], v[78:81]
	v_mfma_f32_16x16x32_bf16 v[70:73], v[160:163], v[242:245], v[70:73]
	v_mfma_f32_16x16x32_bf16 v[126:129], v[144:147], v[202:205], v[126:129]
	v_mfma_f32_16x16x32_bf16 v[118:121], v[164:167], v[202:205], v[118:121]
	v_mfma_f32_16x16x32_bf16 v[110:113], v[144:147], v[210:213], v[110:113]
	v_mfma_f32_16x16x32_bf16 v[102:105], v[164:167], v[210:213], v[102:105]
	v_mfma_f32_16x16x32_bf16 v[94:97], v[144:147], v[238:241], v[94:97]
	v_mfma_f32_16x16x32_bf16 v[86:89], v[164:167], v[238:241], v[86:89]
	v_mfma_f32_16x16x32_bf16 v[78:81], v[144:147], v[246:249], v[78:81]
	v_mfma_f32_16x16x32_bf16 v[70:73], v[164:167], v[246:249], v[70:73]
	s_setprio 0
	s_setprio 1
	v_mfma_f32_16x16x32_bf16 v[122:125], v[168:171], v[198:201], v[122:125]
	v_mfma_f32_16x16x32_bf16 v[114:117], v[176:179], v[198:201], v[114:117]
	v_mfma_f32_16x16x32_bf16 v[106:109], v[168:171], v[206:209], v[106:109]
	v_mfma_f32_16x16x32_bf16 v[98:101], v[176:179], v[206:209], v[98:101]
	v_mfma_f32_16x16x32_bf16 v[90:93], v[168:171], v[234:237], v[90:93]
	v_mfma_f32_16x16x32_bf16 v[82:85], v[176:179], v[234:237], v[82:85]
	v_mfma_f32_16x16x32_bf16 v[74:77], v[168:171], v[242:245], v[74:77]
	v_mfma_f32_16x16x32_bf16 v[66:69], v[176:179], v[242:245], v[66:69]
	v_mfma_f32_16x16x32_bf16 v[122:125], v[172:175], v[202:205], v[122:125]
	v_mfma_f32_16x16x32_bf16 v[114:117], v[194:197], v[202:205], v[114:117]
	v_mfma_f32_16x16x32_bf16 v[106:109], v[172:175], v[210:213], v[106:109]
	v_mfma_f32_16x16x32_bf16 v[98:101], v[194:197], v[210:213], v[98:101]
	v_mfma_f32_16x16x32_bf16 v[90:93], v[172:175], v[238:241], v[90:93]
	v_mfma_f32_16x16x32_bf16 v[82:85], v[194:197], v[238:241], v[82:85]
	v_mfma_f32_16x16x32_bf16 v[74:77], v[172:175], v[246:249], v[74:77]
	v_mfma_f32_16x16x32_bf16 v[66:69], v[194:197], v[246:249], v[66:69]
	s_setprio 0
	s_barrier
; #define PG8_STAGE(bufoff, gbase, voff) do { _Pragma("unroll") for (int _i = 0; _i < 2; ++_i) \
;         __builtin_amdgcn_global_load_lds((const unsigned*)((const char*)(gbase) + (voff)[_i]), (LAS unsigned*)(lds + (bufoff) + ldsw + _i * 8192), 16, 0, 0); } while (0)
; #define PG8_LDA(dst, b, h) do { _Pragma("unroll") for (int m = 0; m < 4; ++m) _Pragma("unroll") for (int k = 0; k < 2; ++k) dst[m][k] = *(const LAS bf16x8*)(lds + PG8_SA(b, h) + aoff + m * 2048 + k * 1024); } while (0)
; #define PG8_LDB(dst, b, h) do { _Pragma("unroll") for (int n = 0; n < 2; ++n) _Pragma("unroll") for (int k = 0; k < 2; ++k) dst[n][k] = *(const LAS bf16x8*)(lds + PG8_SB(b, h) + boff + n * 2048 + k * 1024); } while (0)
; #define PG8_MMA(ai, bj, At, Bt) do { __builtin_amdgcn_s_setprio(1); _Pragma("unroll") for (int m = 0; m < 4; ++m) _Pragma("unroll") for (int n = 0; n < 2; ++n) _Pragma("unroll") for (int k = 0; k < 2; ++k) \
;         acc[ai][bj][m][n] = __builtin_amdgcn_mfma_f32_16x16x32_bf16(Bt[n][k], At[m][k], acc[ai][bj][m][n], 0, 0, 0); __builtin_amdgcn_s_setprio(0); } while (0)
; #define PG8_WAIT_V(n) asm volatile("s_waitcnt vmcnt(" #n ")" ::: "memory")
; #define PG8_WAIT_L(n) asm volatile("s_waitcnt lgkmcnt(" #n ")" ::: "memory")
; #define PG8_BAR __builtin_amdgcn_s_barrier()
; template <class Epi, class Sched, bool ALIGN_EPI = true, bool SP2 = true>
; __device__ __forceinline__ void gemm_phase(LAS unsigned char* lds, const Gemm g, const Sched& S, const Epi& E) {
;     ...
;         for (int t = 0; t < nt; t += 2) {
;             const bool last = (t == nt - 2);
;             const char* a1 = cA + (size_t)(t + 1) * kstep;
;             const char* a2 = last ? nA : cA + (size_t)(t + 2) * kstep; const char* b2 = last ? nB : cB + (size_t)(t + 2) * kstep;
;             const char* a3 = a2 + kstep; const char* b3 = b2 + kstep;
;             if constexpr (SP2) {
;             PG8_LDB(B0, 0, 0); PG8_LDB(B1, 0, 1); PG8_SCHED; PG8_LDA(At, 0, 0); PG8_STAGE(PG8_SA(1, 1), a1 + hstep, voffA);
;             PG8_WAIT_V(8); PG8_WAIT_L(0); PG8_BAR; PG8_MMA(0, 0, At, B0); PG8_MMA(0, 1, At, B1); PG8_BAR; PG8_SCHED;
;     ...
;             PG8_LDA(At, 1, 1); PG8_STAGE(PG8_SB(1, 0), b3, voffB); PG8_STAGE(PG8_SB(1, 1), b3 + hstep, voffB); PG8_STAGE(PG8_SA(1, 0), a3, voffA);
;             PG8_WAIT_V(8); PG8_WAIT_L(0); PG8_BAR; PG8_MMA(1, 0, At, B0); PG8_MMA(1, 1, At, B1); PG8_BAR; PG8_SCHED;
	s_add_i32 s32, s58, s24
	s_add_u32 s8, s8, s92
	s_addc_u32 s9, s9, s93
	s_mov_b32 m0, s32
	ds_read_b128 v[198:201], v159 offset:49152
	ds_read_b128 v[202:205], v159 offset:50176
	ds_read_b128 v[206:209], v159 offset:51200
	ds_read_b128 v[210:213], v159 offset:52224
	ds_read_b128 v[234:237], v159 offset:53248
	ds_read_b128 v[238:241], v159 offset:54272
	ds_read_b128 v[242:245], v159 offset:55296
	ds_read_b128 v[246:249], v159 offset:56320
	global_load_lds_dwordx4 v0, s[8:9]
	s_add_i32 m0, s32, 0x2000
	s_add_i32 s32, s59, s24
	global_load_lds_dwordx4 v130, s[8:9]
	s_add_u32 s8, s8, 0x80000
	s_addc_u32 s9, s9, 0
	s_mov_b32 m0, s32
	s_nop 0
	global_load_lds_dwordx4 v0, s[8:9]
	s_add_i32 m0, s32, 0x2000
	s_nop 0
	global_load_lds_dwordx4 v130, s[8:9]
	s_add_u32 s22, s22, 0xfff80080
	s_addc_u32 s23, s23, -1
	s_mov_b32 m0, s29
	s_nop 0
	global_load_lds_dwordx4 v134, s[22:23]
	s_mov_b32 m0, s30
	s_nop 0
	global_load_lds_dwordx4 v132, s[22:23]
	s_waitcnt vmcnt(8)
	s_waitcnt lgkmcnt(0)
	s_barrier
	s_setprio 1
	s_waitcnt lgkmcnt(0)
	v_mfma_f32_16x16x32_bf16 v[62:65], v[140:143], v[198:201], v[62:65]
	v_mfma_f32_16x16x32_bf16 v[54:57], v[160:163], v[198:201], v[54:57]
	v_mfma_f32_16x16x32_bf16 v[46:49], v[140:143], v[206:209], v[46:49]
	v_mfma_f32_16x16x32_bf16 v[38:41], v[160:163], v[206:209], v[38:41]
	v_mfma_f32_16x16x32_bf16 v[30:33], v[140:143], v[234:237], v[30:33]
	v_mfma_f32_16x16x32_bf16 v[22:25], v[160:163], v[234:237], v[22:25]
	v_mfma_f32_16x16x32_bf16 v[14:17], v[140:143], v[242:245], v[14:17]
	v_mfma_f32_16x16x32_bf16 v[6:9], v[160:163], v[242:245], v[6:9]
	v_mfma_f32_16x16x32_bf16 v[62:65], v[144:147], v[202:205], v[62:65]
	v_mfma_f32_16x16x32_bf16 v[54:57], v[164:167], v[202:205], v[54:57]
	v_mfma_f32_16x16x32_bf16 v[46:49], v[144:147], v[210:213], v[46:49]
	v_mfma_f32_16x16x32_bf16 v[38:41], v[164:167], v[210:213], v[38:41]
	v_mfma_f32_16x16x32_bf16 v[30:33], v[144:147], v[238:241], v[30:33]
	v_mfma_f32_16x16x32_bf16 v[22:25], v[164:167], v[238:241], v[22:25]
	v_mfma_f32_16x16x32_bf16 v[14:17], v[144:147], v[246:249], v[14:17]
	v_mfma_f32_16x16x32_bf16 v[6:9], v[164:167], v[246:249], v[6:9]
	s_setprio 0
	s_setprio 1
	v_mfma_f32_16x16x32_bf16 v[58:61], v[168:171], v[198:201], v[58:61]
	v_mfma_f32_16x16x32_bf16 v[50:53], v[176:179], v[198:201], v[50:53]
	v_mfma_f32_16x16x32_bf16 v[42:45], v[168:171], v[206:209], v[42:45]
	v_mfma_f32_16x16x32_bf16 v[34:37], v[176:179], v[206:209], v[34:37]
	v_mfma_f32_16x16x32_bf16 v[26:29], v[168:171], v[234:237], v[26:29]
	v_mfma_f32_16x16x32_bf16 v[18:21], v[176:179], v[234:237], v[18:21]
	v_mfma_f32_16x16x32_bf16 v[10:13], v[168:171], v[242:245], v[10:13]
	v_mfma_f32_16x16x32_bf16 v[2:5], v[176:179], v[242:245], v[2:5]
	v_mfma_f32_16x16x32_bf16 v[58:61], v[172:175], v[202:205], v[58:61]
	v_mfma_f32_16x16x32_bf16 v[50:53], v[194:197], v[202:205], v[50:53]
	v_mfma_f32_16x16x32_bf16 v[42:45], v[172:175], v[210:213], v[42:45]
	v_mfma_f32_16x16x32_bf16 v[34:37], v[194:197], v[210:213], v[34:37]
	v_mfma_f32_16x16x32_bf16 v[26:29], v[172:175], v[238:241], v[26:29]
	v_mfma_f32_16x16x32_bf16 v[18:21], v[194:197], v[238:241], v[18:21]
	v_mfma_f32_16x16x32_bf16 v[10:13], v[172:175], v[246:249], v[10:13]
	v_mfma_f32_16x16x32_bf16 v[2:5], v[194:197], v[246:249], v[2:5]
	s_setprio 0
	s_barrier
	s_add_i32 s72, s72, 2
	s_add_u32 s6, s6, 0x100
	s_addc_u32 s7, s7, 0
	s_add_u32 s70, s70, 0x100
	s_addc_u32 s71, s71, 0
	s_cmp_gt_u32 s72, 29
.LBB0_94:
	s_add_u32 s8, s6, 0xfff80080
	s_addc_u32 s9, s7, -1
	s_add_i32 s58, 0, 0x10000
	s_cmp_eq_u32 s72, 28
	s_cselect_b32 s23, s17, s9
	s_cselect_b32 s22, s56, s8
	v_add_u32_e32 v148, s58, v153
	s_cselect_b32 s9, s15, s71
	s_cselect_b32 s8, s57, s70
	s_add_i32 s73, 0, 0x14000
	ds_read_b128 v[140:143], v148
	ds_read_b128 v[144:147], v148 offset:1024
	ds_read_b128 v[160:163], v148 offset:2048
	ds_read_b128 v[164:167], v148 offset:3072
	ds_read_b128 v[168:171], v148 offset:16384
	ds_read_b128 v[172:175], v148 offset:17408
	ds_read_b128 v[176:179], v148 offset:18432
	ds_read_b128 v[194:197], v148 offset:19456
	s_add_i32 m0, s25, 0xc000
	ds_read_b128 v[198:201], v159
	ds_read_b128 v[202:205], v159 offset:1024
	ds_read_b128 v[206:209], v159 offset:2048
	ds_read_b128 v[210:213], v159 offset:3072
	ds_read_b128 v[234:237], v159 offset:4096
	ds_read_b128 v[238:241], v159 offset:5120
	ds_read_b128 v[242:245], v159 offset:6144
	ds_read_b128 v[246:249], v159 offset:7168
	global_load_lds_dwordx4 v136, s[6:7]
	s_add_i32 m0, s25, 0xe000
	s_nop 0
	global_load_lds_dwordx4 v138, s[6:7]
	s_waitcnt vmcnt(8)
	s_waitcnt lgkmcnt(0)
	s_barrier
; #define PG8_STAGE(bufoff, gbase, voff) do { _Pragma("unroll") for (int _i = 0; _i < 2; ++_i) \
;         __builtin_amdgcn_global_load_lds((const unsigned*)((const char*)(gbase) + (voff)[_i]), (LAS unsigned*)(lds + (bufoff) + ldsw + _i * 8192), 16, 0, 0); } while (0)
; #define PG8_LDA(dst, b, h) do { _Pragma("unroll") for (int m = 0; m < 4; ++m) _Pragma("unroll") for (int k = 0; k < 2; ++k) dst[m][k] = *(const LAS bf16x8*)(lds + PG8_SA(b, h) + aoff + m * 2048 + k * 1024); } while (0)
; #define PG8_MMA(ai, bj, At, Bt) do { __builtin_amdgcn_s_setprio(1); _Pragma("unroll") for (int m = 0; m < 4; ++m) _Pragma("unroll") for (int n = 0; n < 2; ++n) _Pragma("unroll") for (int k = 0; k < 2; ++k) \
;         acc[ai][bj][m][n] = __builtin_amdgcn_mfma_f32_16x16x32_bf16(Bt[n][k], At[m][k], acc[ai][bj][m][n], 0, 0, 0); __builtin_amdgcn_s_setprio(0); } while (0)
; #define PG8_WAIT_V(n) asm volatile("s_waitcnt vmcnt(" #n ")" ::: "memory")
; #define PG8_WAIT_L(n) asm volatile("s_waitcnt lgkmcnt(" #n ")" ::: "memory")
; #define PG8_BAR __builtin_amdgcn_s_barrier()
; #define PG8_SCHED __builtin_amdgcn_sched_barrier(0)
; template <class Epi, class Sched, bool ALIGN_EPI = true, bool SP2 = true>
; __device__ __forceinline__ void gemm_phase(LAS unsigned char* lds, const Gemm g, const Sched& S, const Epi& E) {
;     ...
;             PG8_WAIT_V(8); PG8_WAIT_L(0); PG8_BAR; PG8_MMA(0, 0, At, B0); PG8_MMA(0, 1, At, B1); PG8_BAR; PG8_SCHED;
;             PG8_LDA(At, 0, 1); PG8_STAGE(PG8_SB(0, 0), b2, voffB); PG8_STAGE(PG8_SB(0, 1), b2 + hstep, voffB); PG8_STAGE(PG8_SA(0, 0), a2, voffA);
;             PG8_WAIT_V(8); PG8_WAIT_L(0); PG8_BAR; PG8_MMA(1, 0, At, B0); PG8_MMA(1, 1, At, B1); PG8_BAR; PG8_SCHED;
	s_setprio 1
	s_waitcnt lgkmcnt(0)
	v_mfma_f32_16x16x32_bf16 v[126:129], v[140:143], v[198:201], v[126:129]
	v_mfma_f32_16x16x32_bf16 v[118:121], v[160:163], v[198:201], v[118:121]
	v_mfma_f32_16x16x32_bf16 v[110:113], v[140:143], v[206:209], v[110:113]
	v_mfma_f32_16x16x32_bf16 v[102:105], v[160:163], v[206:209], v[102:105]
	v_mfma_f32_16x16x32_bf16 v[94:97], v[140:143], v[234:237], v[94:97]
	v_mfma_f32_16x16x32_bf16 v[86:89], v[160:163], v[234:237], v[86:89]
	v_mfma_f32_16x16x32_bf16 v[78:81], v[140:143], v[242:245], v[78:81]
	v_mfma_f32_16x16x32_bf16 v[70:73], v[160:163], v[242:245], v[70:73]
	v_mfma_f32_16x16x32_bf16 v[126:129], v[144:147], v[202:205], v[126:129]
	v_mfma_f32_16x16x32_bf16 v[118:121], v[164:167], v[202:205], v[118:121]
	v_mfma_f32_16x16x32_bf16 v[110:113], v[144:147], v[210:213], v[110:113]
	v_mfma_f32_16x16x32_bf16 v[102:105], v[164:167], v[210:213], v[102:105]
	v_mfma_f32_16x16x32_bf16 v[94:97], v[144:147], v[238:241], v[94:97]
	v_mfma_f32_16x16x32_bf16 v[86:89], v[164:167], v[238:241], v[86:89]
	v_mfma_f32_16x16x32_bf16 v[78:81], v[144:147], v[246:249], v[78:81]
	v_mfma_f32_16x16x32_bf16 v[70:73], v[164:167], v[246:249], v[70:73]
	s_setprio 0
	s_setprio 1
	v_mfma_f32_16x16x32_bf16 v[122:125], v[168:171], v[198:201], v[122:125]
	v_mfma_f32_16x16x32_bf16 v[114:117], v[176:179], v[198:201], v[114:117]
	v_mfma_f32_16x16x32_bf16 v[106:109], v[168:171], v[206:209], v[106:109]
	v_mfma_f32_16x16x32_bf16 v[98:101], v[176:179], v[206:209], v[98:101]
	v_mfma_f32_16x16x32_bf16 v[90:93], v[168:171], v[234:237], v[90:93]
	v_mfma_f32_16x16x32_bf16 v[82:85], v[176:179], v[234:237], v[82:85]
	v_mfma_f32_16x16x32_bf16 v[74:77], v[168:171], v[242:245], v[74:77]
	v_mfma_f32_16x16x32_bf16 v[66:69], v[176:179], v[242:245], v[66:69]
	v_mfma_f32_16x16x32_bf16 v[122:125], v[172:175], v[202:205], v[122:125]
	v_mfma_f32_16x16x32_bf16 v[114:117], v[194:197], v[202:205], v[114:117]
	v_mfma_f32_16x16x32_bf16 v[106:109], v[172:175], v[210:213], v[106:109]
	v_mfma_f32_16x16x32_bf16 v[98:101], v[194:197], v[210:213], v[98:101]
	v_mfma_f32_16x16x32_bf16 v[90:93], v[172:175], v[238:241], v[90:93]
	v_mfma_f32_16x16x32_bf16 v[82:85], v[194:197], v[238:241], v[82:85]
	v_mfma_f32_16x16x32_bf16 v[74:77], v[172:175], v[246:249], v[74:77]
	v_mfma_f32_16x16x32_bf16 v[66:69], v[194:197], v[246:249], v[66:69]
	s_setprio 0
	s_barrier
	s_add_i32 s58, s58, s24
	s_mov_b32 m0, s58
	ds_read_b128 v[198:201], v159 offset:16384
	ds_read_b128 v[202:205], v159 offset:17408
	ds_read_b128 v[206:209], v159 offset:18432
	ds_read_b128 v[210:213], v159 offset:19456
	ds_read_b128 v[234:237], v159 offset:20480
	ds_read_b128 v[238:241], v159 offset:21504
	ds_read_b128 v[242:245], v159 offset:22528
	ds_read_b128 v[246:249], v159 offset:23552
	global_load_lds_dwordx4 v0, s[8:9]
	s_add_i32 m0, s58, 0x2000
	s_add_u32 s58, s8, 0x80000
	s_addc_u32 s59, s9, 0
	s_add_i32 s73, s73, s24
	global_load_lds_dwordx4 v130, s[8:9]
	s_mov_b32 m0, s73
	s_nop 0
	global_load_lds_dwordx4 v0, s[58:59]
	s_add_i32 m0, s73, 0x2000
	s_nop 0
	global_load_lds_dwordx4 v130, s[58:59]
	s_mov_b32 m0, s25
	s_nop 0
	global_load_lds_dwordx4 v134, s[22:23]
	s_mov_b32 m0, s26
	s_nop 0
	global_load_lds_dwordx4 v132, s[22:23]
	s_waitcnt vmcnt(8)
	s_waitcnt lgkmcnt(0)
	s_barrier
	s_setprio 1
	s_waitcnt lgkmcnt(0)
	v_mfma_f32_16x16x32_bf16 v[62:65], v[140:143], v[198:201], v[62:65]
	v_mfma_f32_16x16x32_bf16 v[54:57], v[160:163], v[198:201], v[54:57]
	v_mfma_f32_16x16x32_bf16 v[46:49], v[140:143], v[206:209], v[46:49]
	v_mfma_f32_16x16x32_bf16 v[38:41], v[160:163], v[206:209], v[38:41]
	v_mfma_f32_16x16x32_bf16 v[30:33], v[140:143], v[234:237], v[30:33]
	v_mfma_f32_16x16x32_bf16 v[22:25], v[160:163], v[234:237], v[22:25]
	v_mfma_f32_16x16x32_bf16 v[14:17], v[140:143], v[242:245], v[14:17]
	v_mfma_f32_16x16x32_bf16 v[6:9], v[160:163], v[242:245], v[6:9]
	v_mfma_f32_16x16x32_bf16 v[62:65], v[144:147], v[202:205], v[62:65]
	v_mfma_f32_16x16x32_bf16 v[54:57], v[164:167], v[202:205], v[54:57]
	v_mfma_f32_16x16x32_bf16 v[46:49], v[144:147], v[210:213], v[46:49]
	v_mfma_f32_16x16x32_bf16 v[38:41], v[164:167], v[210:213], v[38:41]
	v_mfma_f32_16x16x32_bf16 v[30:33], v[144:147], v[238:241], v[30:33]
	v_mfma_f32_16x16x32_bf16 v[22:25], v[164:167], v[238:241], v[22:25]
	v_mfma_f32_16x16x32_bf16 v[14:17], v[144:147], v[246:249], v[14:17]
	v_mfma_f32_16x16x32_bf16 v[6:9], v[164:167], v[246:249], v[6:9]
	s_setprio 0
	s_setprio 1
	v_mfma_f32_16x16x32_bf16 v[58:61], v[168:171], v[198:201], v[58:61]
	v_mfma_f32_16x16x32_bf16 v[50:53], v[176:179], v[198:201], v[50:53]
	v_mfma_f32_16x16x32_bf16 v[42:45], v[168:171], v[206:209], v[42:45]
	v_mfma_f32_16x16x32_bf16 v[34:37], v[176:179], v[206:209], v[34:37]
	v_mfma_f32_16x16x32_bf16 v[26:29], v[168:171], v[234:237], v[26:29]
	v_mfma_f32_16x16x32_bf16 v[18:21], v[176:179], v[234:237], v[18:21]
	v_mfma_f32_16x16x32_bf16 v[10:13], v[168:171], v[242:245], v[10:13]
	v_mfma_f32_16x16x32_bf16 v[2:5], v[176:179], v[242:245], v[2:5]
	v_mfma_f32_16x16x32_bf16 v[58:61], v[172:175], v[202:205], v[58:61]
	v_mfma_f32_16x16x32_bf16 v[50:53], v[194:197], v[202:205], v[50:53]
	v_mfma_f32_16x16x32_bf16 v[42:45], v[172:175], v[210:213], v[42:45]
	v_mfma_f32_16x16x32_bf16 v[34:37], v[194:197], v[210:213], v[34:37]
	v_mfma_f32_16x16x32_bf16 v[26:29], v[172:175], v[238:241], v[26:29]
	v_mfma_f32_16x16x32_bf16 v[18:21], v[194:197], v[238:241], v[18:21]
	v_mfma_f32_16x16x32_bf16 v[10:13], v[172:175], v[246:249], v[10:13]
	v_mfma_f32_16x16x32_bf16 v[2:5], v[194:197], v[246:249], v[2:5]
	s_setprio 0
	s_barrier
; #define PG8_STAGE(bufoff, gbase, voff) do { _Pragma("unroll") for (int _i = 0; _i < 2; ++_i) \
;         __builtin_amdgcn_global_load_lds((const unsigned*)((const char*)(gbase) + (voff)[_i]), (LAS unsigned*)(lds + (bufoff) + ldsw + _i * 8192), 16, 0, 0); } while (0)
; #define PG8_LDA(dst, b, h) do { _Pragma("unroll") for (int m = 0; m < 4; ++m) _Pragma("unroll") for (int k = 0; k < 2; ++k) dst[m][k] = *(const LAS bf16x8*)(lds + PG8_SA(b, h) + aoff + m * 2048 + k * 1024); } while (0)
; #define PG8_LDB(dst, b, h) do { _Pragma("unroll") for (int n = 0; n < 2; ++n) _Pragma("unroll") for (int k = 0; k < 2; ++k) dst[n][k] = *(const LAS bf16x8*)(lds + PG8_SB(b, h) + boff + n * 2048 + k * 1024); } while (0)
; #define PG8_MMA(ai, bj, At, Bt) do { __builtin_amdgcn_s_setprio(1); _Pragma("unroll") for (int m = 0; m < 4; ++m) _Pragma("unroll") for (int n = 0; n < 2; ++n) _Pragma("unroll") for (int k = 0; k < 2; ++k) \
;         acc[ai][bj][m][n] = __builtin_amdgcn_mfma_f32_16x16x32_bf16(Bt[n][k], At[m][k], acc[ai][bj][m][n], 0, 0, 0); __builtin_amdgcn_s_setprio(0); } while (0)
; #define PG8_WAIT_V(n) asm volatile("s_waitcnt vmcnt(" #n ")" ::: "memory")
; #define PG8_WAIT_L(n) asm volatile("s_waitcnt lgkmcnt(" #n ")" ::: "memory")
; #define PG8_BAR __builtin_amdgcn_s_barrier()
; #define PG8_SCHED __builtin_amdgcn_sched_barrier(0)
; template <class Epi, class Sched, bool ALIGN_EPI = true, bool SP2 = true>
; __device__ __forceinline__ void gemm_phase(LAS unsigned char* lds, const Gemm g, const Sched& S, const Epi& E) {
;     ...
;             PG8_LDB(B0, 1, 0); PG8_LDB(B1, 1, 1); PG8_SCHED; PG8_LDA(At, 1, 0); PG8_STAGE(PG8_SA(0, 1), a2 + hstep, voffA);
;             PG8_WAIT_V(8); PG8_WAIT_L(0); PG8_BAR; PG8_MMA(0, 0, At, B0); PG8_MMA(0, 1, At, B1); PG8_BAR; PG8_SCHED;
;             PG8_LDA(At, 1, 1); PG8_STAGE(PG8_SB(1, 0), b3, voffB); PG8_STAGE(PG8_SB(1, 1), b3 + hstep, voffB); PG8_STAGE(PG8_SA(1, 0), a3, voffA);
;             PG8_WAIT_V(8); PG8_WAIT_L(0); PG8_BAR; PG8_MMA(1, 0, At, B0); PG8_MMA(1, 1, At, B1); PG8_BAR; PG8_SCHED;
	s_add_i32 s58, 0, 0x18000
	v_add_u32_e32 v150, s58, v153
	s_add_i32 s59, 0, 0x1c000
	ds_read_b128 v[140:143], v150
	ds_read_b128 v[144:147], v150 offset:1024
	ds_read_b128 v[160:163], v150 offset:2048
	ds_read_b128 v[164:167], v150 offset:3072
	ds_read_b128 v[168:171], v150 offset:16384
	ds_read_b128 v[172:175], v150 offset:17408
	ds_read_b128 v[176:179], v150 offset:18432
	ds_read_b128 v[194:197], v150 offset:19456
	s_add_u32 s22, s22, 0x80000
	s_addc_u32 s23, s23, 0
	s_mov_b32 m0, s27
	ds_read_b128 v[198:201], v159 offset:32768
	ds_read_b128 v[202:205], v159 offset:33792
	ds_read_b128 v[206:209], v159 offset:34816
	ds_read_b128 v[210:213], v159 offset:35840
	ds_read_b128 v[234:237], v159 offset:36864
	ds_read_b128 v[238:241], v159 offset:37888
	ds_read_b128 v[242:245], v159 offset:38912
	ds_read_b128 v[246:249], v159 offset:39936
	global_load_lds_dwordx4 v134, s[22:23]
	s_mov_b32 m0, s28
	s_nop 0
	global_load_lds_dwordx4 v132, s[22:23]
	s_waitcnt vmcnt(8)
	s_waitcnt lgkmcnt(0)
	s_barrier
	s_setprio 1
	s_waitcnt lgkmcnt(0)
	v_mfma_f32_16x16x32_bf16 v[126:129], v[140:143], v[198:201], v[126:129]
	v_mfma_f32_16x16x32_bf16 v[118:121], v[160:163], v[198:201], v[118:121]
	v_mfma_f32_16x16x32_bf16 v[110:113], v[140:143], v[206:209], v[110:113]
	v_mfma_f32_16x16x32_bf16 v[102:105], v[160:163], v[206:209], v[102:105]
	v_mfma_f32_16x16x32_bf16 v[94:97], v[140:143], v[234:237], v[94:97]
	v_mfma_f32_16x16x32_bf16 v[86:89], v[160:163], v[234:237], v[86:89]
	v_mfma_f32_16x16x32_bf16 v[78:81], v[140:143], v[242:245], v[78:81]
	v_mfma_f32_16x16x32_bf16 v[70:73], v[160:163], v[242:245], v[70:73]
	v_mfma_f32_16x16x32_bf16 v[126:129], v[144:147], v[202:205], v[126:129]
	v_mfma_f32_16x16x32_bf16 v[118:121], v[164:167], v[202:205], v[118:121]
	v_mfma_f32_16x16x32_bf16 v[110:113], v[144:147], v[210:213], v[110:113]
	v_mfma_f32_16x16x32_bf16 v[102:105], v[164:167], v[210:213], v[102:105]
	v_mfma_f32_16x16x32_bf16 v[94:97], v[144:147], v[238:241], v[94:97]
	v_mfma_f32_16x16x32_bf16 v[86:89], v[164:167], v[238:241], v[86:89]
	v_mfma_f32_16x16x32_bf16 v[78:81], v[144:147], v[246:249], v[78:81]
	v_mfma_f32_16x16x32_bf16 v[70:73], v[164:167], v[246:249], v[70:73]
	s_setprio 0
	s_setprio 1
	v_mfma_f32_16x16x32_bf16 v[122:125], v[168:171], v[198:201], v[122:125]
	v_mfma_f32_16x16x32_bf16 v[114:117], v[176:179], v[198:201], v[114:117]
	v_mfma_f32_16x16x32_bf16 v[106:109], v[168:171], v[206:209], v[106:109]
	v_mfma_f32_16x16x32_bf16 v[98:101], v[176:179], v[206:209], v[98:101]
	v_mfma_f32_16x16x32_bf16 v[90:93], v[168:171], v[234:237], v[90:93]
	v_mfma_f32_16x16x32_bf16 v[82:85], v[176:179], v[234:237], v[82:85]
	v_mfma_f32_16x16x32_bf16 v[74:77], v[168:171], v[242:245], v[74:77]
	v_mfma_f32_16x16x32_bf16 v[66:69], v[176:179], v[242:245], v[66:69]
	v_mfma_f32_16x16x32_bf16 v[122:125], v[172:175], v[202:205], v[122:125]
	v_mfma_f32_16x16x32_bf16 v[114:117], v[194:197], v[202:205], v[114:117]
	v_mfma_f32_16x16x32_bf16 v[106:109], v[172:175], v[210:213], v[106:109]
	v_mfma_f32_16x16x32_bf16 v[98:101], v[194:197], v[210:213], v[98:101]
	v_mfma_f32_16x16x32_bf16 v[90:93], v[172:175], v[238:241], v[90:93]
	v_mfma_f32_16x16x32_bf16 v[82:85], v[194:197], v[238:241], v[82:85]
	v_mfma_f32_16x16x32_bf16 v[74:77], v[172:175], v[246:249], v[74:77]
	v_mfma_f32_16x16x32_bf16 v[66:69], v[194:197], v[246:249], v[66:69]
	s_setprio 0
	s_barrier
	s_add_i32 s32, s58, s24
	s_add_u32 s8, s8, s92
	s_addc_u32 s9, s9, s93
	s_mov_b32 m0, s32
	ds_read_b128 v[198:201], v159 offset:49152
	ds_read_b128 v[202:205], v159 offset:50176
	ds_read_b128 v[206:209], v159 offset:51200
	ds_read_b128 v[210:213], v159 offset:52224
	ds_read_b128 v[234:237], v159 offset:53248
	ds_read_b128 v[238:241], v159 offset:54272
	ds_read_b128 v[242:245], v159 offset:55296
	ds_read_b128 v[246:249], v159 offset:56320
	global_load_lds_dwordx4 v0, s[8:9]
	s_add_i32 m0, s32, 0x2000
	s_add_i32 s32, s59, s24
	global_load_lds_dwordx4 v130, s[8:9]
	s_add_u32 s8, s8, 0x80000
	s_addc_u32 s9, s9, 0
	s_mov_b32 m0, s32
	s_nop 0
	global_load_lds_dwordx4 v0, s[8:9]
	s_add_i32 m0, s32, 0x2000
	s_nop 0
	global_load_lds_dwordx4 v130, s[8:9]
	s_add_u32 s22, s22, 0xfff80080
	s_addc_u32 s23, s23, -1
	s_mov_b32 m0, s29
	s_nop 0
	global_load_lds_dwordx4 v134, s[22:23]
	s_mov_b32 m0, s30
	s_nop 0
	global_load_lds_dwordx4 v132, s[22:23]
	s_waitcnt vmcnt(8)
	s_waitcnt lgkmcnt(0)
	s_barrier
	s_setprio 1
	s_waitcnt lgkmcnt(0)
	v_mfma_f32_16x16x32_bf16 v[62:65], v[140:143], v[198:201], v[62:65]
	v_mfma_f32_16x16x32_bf16 v[54:57], v[160:163], v[198:201], v[54:57]
	v_mfma_f32_16x16x32_bf16 v[46:49], v[140:143], v[206:209], v[46:49]
	v_mfma_f32_16x16x32_bf16 v[38:41], v[160:163], v[206:209], v[38:41]
	v_mfma_f32_16x16x32_bf16 v[30:33], v[140:143], v[234:237], v[30:33]
	v_mfma_f32_16x16x32_bf16 v[22:25], v[160:163], v[234:237], v[22:25]
	v_mfma_f32_16x16x32_bf16 v[14:17], v[140:143], v[242:245], v[14:17]
	v_mfma_f32_16x16x32_bf16 v[6:9], v[160:163], v[242:245], v[6:9]
	v_mfma_f32_16x16x32_bf16 v[62:65], v[144:147], v[202:205], v[62:65]
	v_mfma_f32_16x16x32_bf16 v[54:57], v[164:167], v[202:205], v[54:57]
	v_mfma_f32_16x16x32_bf16 v[46:49], v[144:147], v[210:213], v[46:49]
	v_mfma_f32_16x16x32_bf16 v[38:41], v[164:167], v[210:213], v[38:41]
	v_mfma_f32_16x16x32_bf16 v[30:33], v[144:147], v[238:241], v[30:33]
	v_mfma_f32_16x16x32_bf16 v[22:25], v[164:167], v[238:241], v[22:25]
	v_mfma_f32_16x16x32_bf16 v[14:17], v[144:147], v[246:249], v[14:17]
	v_mfma_f32_16x16x32_bf16 v[6:9], v[164:167], v[246:249], v[6:9]
	s_setprio 0
	s_setprio 1
	v_mfma_f32_16x16x32_bf16 v[58:61], v[168:171], v[198:201], v[58:61]
	v_mfma_f32_16x16x32_bf16 v[50:53], v[176:179], v[198:201], v[50:53]
	v_mfma_f32_16x16x32_bf16 v[42:45], v[168:171], v[206:209], v[42:45]
	v_mfma_f32_16x16x32_bf16 v[34:37], v[176:179], v[206:209], v[34:37]
	v_mfma_f32_16x16x32_bf16 v[26:29], v[168:171], v[234:237], v[26:29]
	v_mfma_f32_16x16x32_bf16 v[18:21], v[176:179], v[234:237], v[18:21]
	v_mfma_f32_16x16x32_bf16 v[10:13], v[168:171], v[242:245], v[10:13]
	v_mfma_f32_16x16x32_bf16 v[2:5], v[176:179], v[242:245], v[2:5]
	v_mfma_f32_16x16x32_bf16 v[58:61], v[172:175], v[202:205], v[58:61]
	v_mfma_f32_16x16x32_bf16 v[50:53], v[194:197], v[202:205], v[50:53]
	v_mfma_f32_16x16x32_bf16 v[42:45], v[172:175], v[210:213], v[42:45]
	v_mfma_f32_16x16x32_bf16 v[34:37], v[194:197], v[210:213], v[34:37]
	v_mfma_f32_16x16x32_bf16 v[26:29], v[172:175], v[238:241], v[26:29]
	v_mfma_f32_16x16x32_bf16 v[18:21], v[194:197], v[238:241], v[18:21]
	v_mfma_f32_16x16x32_bf16 v[10:13], v[172:175], v[246:249], v[10:13]
	v_mfma_f32_16x16x32_bf16 v[2:5], v[194:197], v[246:249], v[2:5]
	s_setprio 0
	s_barrier
	s_add_i32 s72, s72, 2
	s_add_u32 s6, s6, 0x100
	s_addc_u32 s7, s7, 0
	s_add_u32 s70, s70, 0x100
	s_addc_u32 s71, s71, 0
	s_cmp_gt_u32 s72, 29
	s_cbranch_scc0 .LBB0_94
	s_and_b64 vcc, exec, s[12:13]
	s_cbranch_vccz .LBB0_97
	s_barrier

;     __device__ bool next(int i, Unit& u) const { if (!so.next(i >> 1, u)) return false; u.kind = i & 1; return true; }
; #define PG8_STAGE(bufoff, gbase, voff) do { _Pragma("unroll") for (int _i = 0; _i < 2; ++_i) \
;         __builtin_amdgcn_global_load_lds((const unsigned*)((const char*)(gbase) + (voff)[_i]), (LAS unsigned*)(lds + (bufoff) + ldsw + _i * 8192), 16, 0, 0); } while (0)
; #define PG8_LDA(dst, b, h) do { _Pragma("unroll") for (int m = 0; m < 4; ++m) _Pragma("unroll") for (int k = 0; k < 2; ++k) dst[m][k] = *(const LAS bf16x8*)(lds + PG8_SA(b, h) + aoff + m * 2048 + k * 1024); } while (0)
; #define PG8_LDB(dst, b, h) do { _Pragma("unroll") for (int n = 0; n < 2; ++n) _Pragma("unroll") for (int k = 0; k < 2; ++k) dst[n][k] = *(const LAS bf16x8*)(lds + PG8_SB(b, h) + boff + n * 2048 + k * 1024); } while (0)
; #define PG8_WAIT_V(n) asm volatile("s_waitcnt vmcnt(" #n ")" ::: "memory")
; #define PG8_WAIT_L(n) asm volatile("s_waitcnt lgkmcnt(" #n ")" ::: "memory")
; #define PG8_BAR __builtin_amdgcn_s_barrier()
; template <class Epi, class Sched, bool ALIGN_EPI = true, bool SP2 = true>
; __device__ __forceinline__ void gemm_phase(LAS unsigned char* lds, const Gemm g, const Sched& S, const Epi& E) {
;     ...
;         const bool has_next = S.next(ui + 1, nxt);
;         const char* nA = has_next ? (const char*)(nxt.kind ? g.A1 : g.A0) + (size_t)nxt.pm * tstep : cA; const char* nB = has_next ? (const char*)(nxt.kind ? g.B1 : g.B0) + (size_t)nxt.pn * tstep : cB;
;         for (int t = 0; t < nt; t += 2) {
;             const bool last = (t == nt - 2);
;             const char* a1 = cA + (size_t)(t + 1) * kstep;
;             const char* a2 = last ? nA : cA + (size_t)(t + 2) * kstep; const char* b2 = last ? nB : cB + (size_t)(t + 2) * kstep;
;             const char* a3 = a2 + kstep; const char* b3 = b2 + kstep;
;             if constexpr (SP2) {
;             PG8_LDB(B0, 0, 0); PG8_LDB(B1, 0, 1); PG8_SCHED; PG8_LDA(At, 0, 0); PG8_STAGE(PG8_SA(1, 1), a1 + hstep, voffA);
;             PG8_WAIT_V(8); PG8_WAIT_L(0); PG8_BAR; PG8_MMA(0, 0, At, B0); PG8_MMA(0, 1, At, B1); PG8_BAR; PG8_SCHED;
;             PG8_LDA(At, 0, 1); PG8_STAGE(PG8_SB(0, 0), b2, voffB); PG8_STAGE(PG8_SB(0, 1), b2 + hstep, voffB); PG8_STAGE(PG8_SA(0, 0), a2, voffA);
;             PG8_WAIT_V(8); PG8_WAIT_L(0); PG8_BAR; PG8_MMA(1, 0, At, B0); PG8_MMA(1, 1, At, B1); PG8_BAR; PG8_SCHED;
.LBB0_305:
	s_ashr_i32 s9, s8, 31
	s_lshl_b64 s[12:13], s[8:9], 20
	s_add_u32 s12, s88, s12
	s_addc_u32 s13, s89, s13
	s_and_b64 s[14:15], s[10:11], exec
	s_cselect_b32 s9, s13, s17
	s_cselect_b32 s70, s12, s16
	s_ashr_i32 s7, s6, 31
	s_lshl_b64 s[14:15], s[6:7], 20
	s_add_u32 s14, s24, s14
	s_addc_u32 s15, s25, s15
	s_and_b64 s[22:23], s[10:11], exec
	s_cselect_b32 s7, s15, s21
	s_cselect_b32 s71, s14, s20
	s_add_u32 s16, s16, 0x80080
	s_addc_u32 s17, s17, 0
	s_add_u32 s72, s20, 0x100
	s_addc_u32 s73, s21, 0
	s_mov_b32 s74, -2
	s_add_u32 s20, s16, 0xfff80080
	s_addc_u32 s21, s17, -1
	s_add_i32 s58, 0, 0x10000
	s_cmp_eq_u32 s74, 28
	s_cselect_b32 s23, s9, s21
	s_cselect_b32 s22, s70, s20
	v_add_u32_e32 v144, s58, v147
	s_cselect_b32 s21, s7, s73
	s_cselect_b32 s20, s71, s72
	s_add_i32 s75, 0, 0x14000
	ds_read_b128 v[140:143], v144
	ds_read_b128 v[154:157], v144 offset:1024
	ds_read_b128 v[158:161], v144 offset:2048
	ds_read_b128 v[162:165], v144 offset:3072
	ds_read_b128 v[166:169], v144 offset:16384
	ds_read_b128 v[170:173], v144 offset:17408
	ds_read_b128 v[174:177], v144 offset:18432
	ds_read_b128 v[194:197], v144 offset:19456
	s_add_i32 m0, s27, 0xc000
	ds_read_b128 v[198:201], v153
	ds_read_b128 v[202:205], v153 offset:1024
	ds_read_b128 v[206:209], v153 offset:2048
	ds_read_b128 v[210:213], v153 offset:3072
	ds_read_b128 v[234:237], v153 offset:4096
	ds_read_b128 v[238:241], v153 offset:5120
	ds_read_b128 v[242:245], v153 offset:6144
	ds_read_b128 v[246:249], v153 offset:7168
	global_load_lds_dwordx4 v136, s[16:17]
	s_add_i32 m0, s27, 0xe000
	s_nop 0
	global_load_lds_dwordx4 v138, s[16:17]
	s_waitcnt vmcnt(8)
	s_waitcnt lgkmcnt(0)
	s_barrier
	s_setprio 1
	s_waitcnt lgkmcnt(0)
	v_mfma_f32_16x16x32_bf16 v[126:129], v[140:143], v[198:201], 0
	v_mfma_f32_16x16x32_bf16 v[122:125], v[158:161], v[198:201], 0
	v_mfma_f32_16x16x32_bf16 v[114:117], v[140:143], v[206:209], 0
	v_mfma_f32_16x16x32_bf16 v[106:109], v[158:161], v[206:209], 0
	v_mfma_f32_16x16x32_bf16 v[98:101], v[140:143], v[234:237], 0
	v_mfma_f32_16x16x32_bf16 v[90:93], v[158:161], v[234:237], 0
	v_mfma_f32_16x16x32_bf16 v[82:85], v[140:143], v[242:245], 0
	v_mfma_f32_16x16x32_bf16 v[74:77], v[158:161], v[242:245], 0
	v_mfma_f32_16x16x32_bf16 v[126:129], v[154:157], v[202:205], v[126:129]
	v_mfma_f32_16x16x32_bf16 v[122:125], v[162:165], v[202:205], v[122:125]
	v_mfma_f32_16x16x32_bf16 v[114:117], v[154:157], v[210:213], v[114:117]
	v_mfma_f32_16x16x32_bf16 v[106:109], v[162:165], v[210:213], v[106:109]
	v_mfma_f32_16x16x32_bf16 v[98:101], v[154:157], v[238:241], v[98:101]
	v_mfma_f32_16x16x32_bf16 v[90:93], v[162:165], v[238:241], v[90:93]
	v_mfma_f32_16x16x32_bf16 v[82:85], v[154:157], v[246:249], v[82:85]
	v_mfma_f32_16x16x32_bf16 v[74:77], v[162:165], v[246:249], v[74:77]
	s_setprio 0
	s_setprio 1
	v_mfma_f32_16x16x32_bf16 v[118:121], v[166:169], v[198:201], 0
	v_mfma_f32_16x16x32_bf16 v[110:113], v[174:177], v[198:201], 0
	v_mfma_f32_16x16x32_bf16 v[102:105], v[166:169], v[206:209], 0
	v_mfma_f32_16x16x32_bf16 v[94:97], v[174:177], v[206:209], 0
	v_mfma_f32_16x16x32_bf16 v[86:89], v[166:169], v[234:237], 0
	v_mfma_f32_16x16x32_bf16 v[78:81], v[174:177], v[234:237], 0
	v_mfma_f32_16x16x32_bf16 v[70:73], v[166:169], v[242:245], 0
	v_mfma_f32_16x16x32_bf16 v[66:69], v[174:177], v[242:245], 0
	v_mfma_f32_16x16x32_bf16 v[118:121], v[170:173], v[202:205], v[118:121]
	v_mfma_f32_16x16x32_bf16 v[110:113], v[194:197], v[202:205], v[110:113]
	v_mfma_f32_16x16x32_bf16 v[102:105], v[170:173], v[210:213], v[102:105]
	v_mfma_f32_16x16x32_bf16 v[94:97], v[194:197], v[210:213], v[94:97]
	v_mfma_f32_16x16x32_bf16 v[86:89], v[170:173], v[238:241], v[86:89]
	v_mfma_f32_16x16x32_bf16 v[78:81], v[194:197], v[238:241], v[78:81]
	v_mfma_f32_16x16x32_bf16 v[70:73], v[170:173], v[246:249], v[70:73]
	v_mfma_f32_16x16x32_bf16 v[66:69], v[194:197], v[246:249], v[66:69]
	s_setprio 0
	s_barrier
	s_add_i32 s58, s58, s26
	s_mov_b32 m0, s58
	ds_read_b128 v[198:201], v153 offset:16384
	ds_read_b128 v[202:205], v153 offset:17408
	ds_read_b128 v[206:209], v153 offset:18432
	ds_read_b128 v[210:213], v153 offset:19456
	ds_read_b128 v[234:237], v153 offset:20480
	ds_read_b128 v[238:241], v153 offset:21504
	ds_read_b128 v[242:245], v153 offset:22528
	ds_read_b128 v[246:249], v153 offset:23552
	global_load_lds_dwordx4 v0, s[20:21]
	s_add_i32 m0, s58, 0x2000
	s_add_u32 s58, s20, 0x80000
	s_addc_u32 s59, s21, 0
	s_add_i32 s75, s75, s26
	global_load_lds_dwordx4 v130, s[20:21]
	s_mov_b32 m0, s75
	s_nop 0
	global_load_lds_dwordx4 v0, s[58:59]
	s_add_i32 m0, s75, 0x2000
	s_nop 0
	global_load_lds_dwordx4 v130, s[58:59]
	s_mov_b32 m0, s27
	s_nop 0
	global_load_lds_dwordx4 v134, s[22:23]
	s_mov_b32 m0, s28
	s_nop 0
	global_load_lds_dwordx4 v132, s[22:23]
	s_waitcnt vmcnt(8)
	s_waitcnt lgkmcnt(0)
	s_barrier
; #define PG8_STAGE(bufoff, gbase, voff) do { _Pragma("unroll") for (int _i = 0; _i < 2; ++_i) \
;         __builtin_amdgcn_global_load_lds((const unsigned*)((const char*)(gbase) + (voff)[_i]), (LAS unsigned*)(lds + (bufoff) + ldsw + _i * 8192), 16, 0, 0); } while (0)
; #define PG8_LDA(dst, b, h) do { _Pragma("unroll") for (int m = 0; m < 4; ++m) _Pragma("unroll") for (int k = 0; k < 2; ++k) dst[m][k] = *(const LAS bf16x8*)(lds + PG8_SA(b, h) + aoff + m * 2048 + k * 1024); } while (0)
; #define PG8_LDB(dst, b, h) do { _Pragma("unroll") for (int n = 0; n < 2; ++n) _Pragma("unroll") for (int k = 0; k < 2; ++k) dst[n][k] = *(const LAS bf16x8*)(lds + PG8_SB(b, h) + boff + n * 2048 + k * 1024); } while (0)
; #define PG8_MMA(ai, bj, At, Bt) do { __builtin_amdgcn_s_setprio(1); _Pragma("unroll") for (int m = 0; m < 4; ++m) _Pragma("unroll") for (int n = 0; n < 2; ++n) _Pragma("unroll") for (int k = 0; k < 2; ++k) \
;         acc[ai][bj][m][n] = __builtin_amdgcn_mfma_f32_16x16x32_bf16(Bt[n][k], At[m][k], acc[ai][bj][m][n], 0, 0, 0); __builtin_amdgcn_s_setprio(0); } while (0)
; #define PG8_WAIT_V(n) asm volatile("s_waitcnt vmcnt(" #n ")" ::: "memory")
; #define PG8_WAIT_L(n) asm volatile("s_waitcnt lgkmcnt(" #n ")" ::: "memory")
; #define PG8_BAR __builtin_amdgcn_s_barrier()
; #define PG8_SCHED __builtin_amdgcn_sched_barrier(0)
; template <class Epi, class Sched, bool ALIGN_EPI = true, bool SP2 = true>
; __device__ __forceinline__ void gemm_phase(LAS unsigned char* lds, const Gemm g, const Sched& S, const Epi& E) {
;     ...
;             PG8_WAIT_V(8); PG8_WAIT_L(0); PG8_BAR; PG8_MMA(1, 0, At, B0); PG8_MMA(1, 1, At, B1); PG8_BAR; PG8_SCHED;
;             PG8_LDB(B0, 1, 0); PG8_LDB(B1, 1, 1); PG8_SCHED; PG8_LDA(At, 1, 0); PG8_STAGE(PG8_SA(0, 1), a2 + hstep, voffA);
;             PG8_WAIT_V(8); PG8_WAIT_L(0); PG8_BAR; PG8_MMA(0, 0, At, B0); PG8_MMA(0, 1, At, B1); PG8_BAR; PG8_SCHED;
;             PG8_LDA(At, 1, 1); PG8_STAGE(PG8_SB(1, 0), b3, voffB); PG8_STAGE(PG8_SB(1, 1), b3 + hstep, voffB); PG8_STAGE(PG8_SA(1, 0), a3, voffA);
	s_setprio 1
	s_waitcnt lgkmcnt(0)
	v_mfma_f32_16x16x32_bf16 v[62:65], v[140:143], v[198:201], 0
	v_mfma_f32_16x16x32_bf16 v[58:61], v[158:161], v[198:201], 0
	v_mfma_f32_16x16x32_bf16 v[50:53], v[140:143], v[206:209], 0
	v_mfma_f32_16x16x32_bf16 v[42:45], v[158:161], v[206:209], 0
	v_mfma_f32_16x16x32_bf16 v[34:37], v[140:143], v[234:237], 0
	v_mfma_f32_16x16x32_bf16 v[26:29], v[158:161], v[234:237], 0
	v_mfma_f32_16x16x32_bf16 v[18:21], v[140:143], v[242:245], 0
	v_mfma_f32_16x16x32_bf16 v[10:13], v[158:161], v[242:245], 0
	v_mfma_f32_16x16x32_bf16 v[62:65], v[154:157], v[202:205], v[62:65]
	v_mfma_f32_16x16x32_bf16 v[58:61], v[162:165], v[202:205], v[58:61]
	v_mfma_f32_16x16x32_bf16 v[50:53], v[154:157], v[210:213], v[50:53]
	v_mfma_f32_16x16x32_bf16 v[42:45], v[162:165], v[210:213], v[42:45]
	v_mfma_f32_16x16x32_bf16 v[34:37], v[154:157], v[238:241], v[34:37]
	v_mfma_f32_16x16x32_bf16 v[26:29], v[162:165], v[238:241], v[26:29]
	v_mfma_f32_16x16x32_bf16 v[18:21], v[154:157], v[246:249], v[18:21]
	v_mfma_f32_16x16x32_bf16 v[10:13], v[162:165], v[246:249], v[10:13]
	s_setprio 0
	s_setprio 1
	v_mfma_f32_16x16x32_bf16 v[54:57], v[166:169], v[198:201], 0
	v_mfma_f32_16x16x32_bf16 v[46:49], v[174:177], v[198:201], 0
	v_mfma_f32_16x16x32_bf16 v[38:41], v[166:169], v[206:209], 0
	v_mfma_f32_16x16x32_bf16 v[30:33], v[174:177], v[206:209], 0
	v_mfma_f32_16x16x32_bf16 v[22:25], v[166:169], v[234:237], 0
	v_mfma_f32_16x16x32_bf16 v[14:17], v[174:177], v[234:237], 0
	v_mfma_f32_16x16x32_bf16 v[6:9], v[166:169], v[242:245], 0
	v_mfma_f32_16x16x32_bf16 v[2:5], v[174:177], v[242:245], 0
	v_mfma_f32_16x16x32_bf16 v[54:57], v[170:173], v[202:205], v[54:57]
	v_mfma_f32_16x16x32_bf16 v[46:49], v[194:197], v[202:205], v[46:49]
	v_mfma_f32_16x16x32_bf16 v[38:41], v[170:173], v[210:213], v[38:41]
	v_mfma_f32_16x16x32_bf16 v[30:33], v[194:197], v[210:213], v[30:33]
	v_mfma_f32_16x16x32_bf16 v[22:25], v[170:173], v[238:241], v[22:25]
	v_mfma_f32_16x16x32_bf16 v[14:17], v[194:197], v[238:241], v[14:17]
	v_mfma_f32_16x16x32_bf16 v[6:9], v[170:173], v[246:249], v[6:9]
	v_mfma_f32_16x16x32_bf16 v[2:5], v[194:197], v[246:249], v[2:5]
	s_setprio 0
	s_barrier
	s_add_i32 s58, 0, 0x18000
	v_add_u32_e32 v144, s58, v147
	s_add_i32 s59, 0, 0x1c000
	ds_read_b128 v[140:143], v144
	ds_read_b128 v[154:157], v144 offset:1024
	ds_read_b128 v[158:161], v144 offset:2048
	ds_read_b128 v[162:165], v144 offset:3072
	ds_read_b128 v[166:169], v144 offset:16384
	ds_read_b128 v[170:173], v144 offset:17408
	ds_read_b128 v[174:177], v144 offset:18432
	ds_read_b128 v[194:197], v144 offset:19456
	s_add_u32 s22, s22, 0x80000
	s_addc_u32 s23, s23, 0
	s_mov_b32 m0, s29
	ds_read_b128 v[198:201], v153 offset:32768
	ds_read_b128 v[202:205], v153 offset:33792
	ds_read_b128 v[206:209], v153 offset:34816
	ds_read_b128 v[210:213], v153 offset:35840
	ds_read_b128 v[234:237], v153 offset:36864
	ds_read_b128 v[238:241], v153 offset:37888
	ds_read_b128 v[242:245], v153 offset:38912
	ds_read_b128 v[246:249], v153 offset:39936
	global_load_lds_dwordx4 v134, s[22:23]
	s_mov_b32 m0, s30
	s_nop 0
	global_load_lds_dwordx4 v132, s[22:23]
	s_waitcnt vmcnt(8)
	s_waitcnt lgkmcnt(0)
	s_barrier
	s_setprio 1
	s_waitcnt lgkmcnt(0)
	v_mfma_f32_16x16x32_bf16 v[126:129], v[140:143], v[198:201], v[126:129]
	v_mfma_f32_16x16x32_bf16 v[122:125], v[158:161], v[198:201], v[122:125]
	v_mfma_f32_16x16x32_bf16 v[114:117], v[140:143], v[206:209], v[114:117]
	v_mfma_f32_16x16x32_bf16 v[106:109], v[158:161], v[206:209], v[106:109]
	v_mfma_f32_16x16x32_bf16 v[98:101], v[140:143], v[234:237], v[98:101]
	v_mfma_f32_16x16x32_bf16 v[90:93], v[158:161], v[234:237], v[90:93]
	v_mfma_f32_16x16x32_bf16 v[82:85], v[140:143], v[242:245], v[82:85]
	v_mfma_f32_16x16x32_bf16 v[74:77], v[158:161], v[242:245], v[74:77]
	v_mfma_f32_16x16x32_bf16 v[126:129], v[154:157], v[202:205], v[126:129]
	v_mfma_f32_16x16x32_bf16 v[122:125], v[162:165], v[202:205], v[122:125]
	v_mfma_f32_16x16x32_bf16 v[114:117], v[154:157], v[210:213], v[114:117]
	v_mfma_f32_16x16x32_bf16 v[106:109], v[162:165], v[210:213], v[106:109]
	v_mfma_f32_16x16x32_bf16 v[98:101], v[154:157], v[238:241], v[98:101]
	v_mfma_f32_16x16x32_bf16 v[90:93], v[162:165], v[238:241], v[90:93]
	v_mfma_f32_16x16x32_bf16 v[82:85], v[154:157], v[246:249], v[82:85]
	v_mfma_f32_16x16x32_bf16 v[74:77], v[162:165], v[246:249], v[74:77]
	s_setprio 0
	s_setprio 1
	v_mfma_f32_16x16x32_bf16 v[118:121], v[166:169], v[198:201], v[118:121]
	v_mfma_f32_16x16x32_bf16 v[110:113], v[174:177], v[198:201], v[110:113]
	v_mfma_f32_16x16x32_bf16 v[102:105], v[166:169], v[206:209], v[102:105]
	v_mfma_f32_16x16x32_bf16 v[94:97], v[174:177], v[206:209], v[94:97]
	v_mfma_f32_16x16x32_bf16 v[86:89], v[166:169], v[234:237], v[86:89]
	v_mfma_f32_16x16x32_bf16 v[78:81], v[174:177], v[234:237], v[78:81]
	v_mfma_f32_16x16x32_bf16 v[70:73], v[166:169], v[242:245], v[70:73]
	v_mfma_f32_16x16x32_bf16 v[66:69], v[174:177], v[242:245], v[66:69]
	v_mfma_f32_16x16x32_bf16 v[118:121], v[170:173], v[202:205], v[118:121]
	v_mfma_f32_16x16x32_bf16 v[110:113], v[194:197], v[202:205], v[110:113]
	v_mfma_f32_16x16x32_bf16 v[102:105], v[170:173], v[210:213], v[102:105]
	v_mfma_f32_16x16x32_bf16 v[94:97], v[194:197], v[210:213], v[94:97]
	v_mfma_f32_16x16x32_bf16 v[86:89], v[170:173], v[238:241], v[86:89]
	v_mfma_f32_16x16x32_bf16 v[78:81], v[194:197], v[238:241], v[78:81]
	v_mfma_f32_16x16x32_bf16 v[70:73], v[170:173], v[246:249], v[70:73]
	v_mfma_f32_16x16x32_bf16 v[66:69], v[194:197], v[246:249], v[66:69]
	s_setprio 0
	s_barrier
; #define PG8_STAGE(bufoff, gbase, voff) do { _Pragma("unroll") for (int _i = 0; _i < 2; ++_i) \
;         __builtin_amdgcn_global_load_lds((const unsigned*)((const char*)(gbase) + (voff)[_i]), (LAS unsigned*)(lds + (bufoff) + ldsw + _i * 8192), 16, 0, 0); } while (0)
; #define PG8_LDA(dst, b, h) do { _Pragma("unroll") for (int m = 0; m < 4; ++m) _Pragma("unroll") for (int k = 0; k < 2; ++k) dst[m][k] = *(const LAS bf16x8*)(lds + PG8_SA(b, h) + aoff + m * 2048 + k * 1024); } while (0)
; #define PG8_LDB(dst, b, h) do { _Pragma("unroll") for (int n = 0; n < 2; ++n) _Pragma("unroll") for (int k = 0; k < 2; ++k) dst[n][k] = *(const LAS bf16x8*)(lds + PG8_SB(b, h) + boff + n * 2048 + k * 1024); } while (0)
; #define PG8_MMA(ai, bj, At, Bt) do { __builtin_amdgcn_s_setprio(1); _Pragma("unroll") for (int m = 0; m < 4; ++m) _Pragma("unroll") for (int n = 0; n < 2; ++n) _Pragma("unroll") for (int k = 0; k < 2; ++k) \
;         acc[ai][bj][m][n] = __builtin_amdgcn_mfma_f32_16x16x32_bf16(Bt[n][k], At[m][k], acc[ai][bj][m][n], 0, 0, 0); __builtin_amdgcn_s_setprio(0); } while (0)
; #define PG8_WAIT_V(n) asm volatile("s_waitcnt vmcnt(" #n ")" ::: "memory")
; #define PG8_WAIT_L(n) asm volatile("s_waitcnt lgkmcnt(" #n ")" ::: "memory")
; #define PG8_BAR __builtin_amdgcn_s_barrier()
; template <class Epi, class Sched, bool ALIGN_EPI = true, bool SP2 = true>
; __device__ __forceinline__ void gemm_phase(LAS unsigned char* lds, const Gemm g, const Sched& S, const Epi& E) {
;     ...
;         for (int t = 0; t < nt; t += 2) {
;             const bool last = (t == nt - 2);
;             const char* a1 = cA + (size_t)(t + 1) * kstep;
;             const char* a2 = last ? nA : cA + (size_t)(t + 2) * kstep; const char* b2 = last ? nB : cB + (size_t)(t + 2) * kstep;
;             const char* a3 = a2 + kstep; const char* b3 = b2 + kstep;
;             if constexpr (SP2) {
;             PG8_LDB(B0, 0, 0); PG8_LDB(B1, 0, 1); PG8_SCHED; PG8_LDA(At, 0, 0); PG8_STAGE(PG8_SA(1, 1), a1 + hstep, voffA);
;             PG8_WAIT_V(8); PG8_WAIT_L(0); PG8_BAR; PG8_MMA(0, 0, At, B0); PG8_MMA(0, 1, At, B1); PG8_BAR; PG8_SCHED;
;     ...
;             PG8_LDA(At, 1, 1); PG8_STAGE(PG8_SB(1, 0), b3, voffB); PG8_STAGE(PG8_SB(1, 1), b3 + hstep, voffB); PG8_STAGE(PG8_SA(1, 0), a3, voffA);
;             PG8_WAIT_V(8); PG8_WAIT_L(0); PG8_BAR; PG8_MMA(1, 0, At, B0); PG8_MMA(1, 1, At, B1); PG8_BAR; PG8_SCHED;
	s_add_i32 s32, s58, s26
	s_add_u32 s20, s20, s92
	s_addc_u32 s21, s21, s93
	s_mov_b32 m0, s32
	ds_read_b128 v[198:201], v153 offset:49152
	ds_read_b128 v[202:205], v153 offset:50176
	ds_read_b128 v[206:209], v153 offset:51200
	ds_read_b128 v[210:213], v153 offset:52224
	ds_read_b128 v[234:237], v153 offset:53248
	ds_read_b128 v[238:241], v153 offset:54272
	ds_read_b128 v[242:245], v153 offset:55296
	ds_read_b128 v[246:249], v153 offset:56320
	global_load_lds_dwordx4 v0, s[20:21]
	s_add_i32 m0, s32, 0x2000
	s_add_i32 s32, s59, s26
	global_load_lds_dwordx4 v130, s[20:21]
	s_add_u32 s20, s20, 0x80000
	s_addc_u32 s21, s21, 0
	s_mov_b32 m0, s32
	s_nop 0
	global_load_lds_dwordx4 v0, s[20:21]
	s_add_i32 m0, s32, 0x2000
	s_nop 0
	global_load_lds_dwordx4 v130, s[20:21]
	s_add_u32 s22, s22, 0xfff80080
	s_addc_u32 s23, s23, -1
	s_mov_b32 m0, s31
	s_nop 0
	global_load_lds_dwordx4 v134, s[22:23]
	s_mov_b32 m0, s34
	s_nop 0
	global_load_lds_dwordx4 v132, s[22:23]
	s_waitcnt vmcnt(8)
	s_waitcnt lgkmcnt(0)
	s_barrier
	s_setprio 1
	s_waitcnt lgkmcnt(0)
	v_mfma_f32_16x16x32_bf16 v[62:65], v[140:143], v[198:201], v[62:65]
	v_mfma_f32_16x16x32_bf16 v[58:61], v[158:161], v[198:201], v[58:61]
	v_mfma_f32_16x16x32_bf16 v[50:53], v[140:143], v[206:209], v[50:53]
	v_mfma_f32_16x16x32_bf16 v[42:45], v[158:161], v[206:209], v[42:45]
	v_mfma_f32_16x16x32_bf16 v[34:37], v[140:143], v[234:237], v[34:37]
	v_mfma_f32_16x16x32_bf16 v[26:29], v[158:161], v[234:237], v[26:29]
	v_mfma_f32_16x16x32_bf16 v[18:21], v[140:143], v[242:245], v[18:21]
	v_mfma_f32_16x16x32_bf16 v[10:13], v[158:161], v[242:245], v[10:13]
	v_mfma_f32_16x16x32_bf16 v[62:65], v[154:157], v[202:205], v[62:65]
	v_mfma_f32_16x16x32_bf16 v[58:61], v[162:165], v[202:205], v[58:61]
	v_mfma_f32_16x16x32_bf16 v[50:53], v[154:157], v[210:213], v[50:53]
	v_mfma_f32_16x16x32_bf16 v[42:45], v[162:165], v[210:213], v[42:45]
	v_mfma_f32_16x16x32_bf16 v[34:37], v[154:157], v[238:241], v[34:37]
	v_mfma_f32_16x16x32_bf16 v[26:29], v[162:165], v[238:241], v[26:29]
	v_mfma_f32_16x16x32_bf16 v[18:21], v[154:157], v[246:249], v[18:21]
	v_mfma_f32_16x16x32_bf16 v[10:13], v[162:165], v[246:249], v[10:13]
	s_setprio 0
	s_setprio 1
	v_mfma_f32_16x16x32_bf16 v[54:57], v[166:169], v[198:201], v[54:57]
	v_mfma_f32_16x16x32_bf16 v[46:49], v[174:177], v[198:201], v[46:49]
	v_mfma_f32_16x16x32_bf16 v[38:41], v[166:169], v[206:209], v[38:41]
	v_mfma_f32_16x16x32_bf16 v[30:33], v[174:177], v[206:209], v[30:33]
	v_mfma_f32_16x16x32_bf16 v[22:25], v[166:169], v[234:237], v[22:25]
	v_mfma_f32_16x16x32_bf16 v[14:17], v[174:177], v[234:237], v[14:17]
	v_mfma_f32_16x16x32_bf16 v[6:9], v[166:169], v[242:245], v[6:9]
	v_mfma_f32_16x16x32_bf16 v[2:5], v[174:177], v[242:245], v[2:5]
	v_mfma_f32_16x16x32_bf16 v[54:57], v[170:173], v[202:205], v[54:57]
	v_mfma_f32_16x16x32_bf16 v[46:49], v[194:197], v[202:205], v[46:49]
	v_mfma_f32_16x16x32_bf16 v[38:41], v[170:173], v[210:213], v[38:41]
	v_mfma_f32_16x16x32_bf16 v[30:33], v[194:197], v[210:213], v[30:33]
	v_mfma_f32_16x16x32_bf16 v[22:25], v[170:173], v[238:241], v[22:25]
	v_mfma_f32_16x16x32_bf16 v[14:17], v[194:197], v[238:241], v[14:17]
	v_mfma_f32_16x16x32_bf16 v[6:9], v[170:173], v[246:249], v[6:9]
	v_mfma_f32_16x16x32_bf16 v[2:5], v[194:197], v[246:249], v[2:5]
	s_setprio 0
	s_barrier
	s_add_i32 s74, s74, 2
	s_add_u32 s16, s16, 0x100
	s_addc_u32 s17, s17, 0
	s_add_u32 s72, s72, 0x100
	s_addc_u32 s73, s73, 0
	s_cmp_gt_u32 s74, 29
.LBB0_306:
	s_add_u32 s20, s16, 0xfff80080
	s_addc_u32 s21, s17, -1
	s_add_i32 s58, 0, 0x10000
	s_cmp_eq_u32 s74, 28
	s_cselect_b32 s23, s9, s21
	s_cselect_b32 s22, s70, s20
	v_add_u32_e32 v144, s58, v147
	s_cselect_b32 s21, s7, s73
	s_cselect_b32 s20, s71, s72
	s_add_i32 s75, 0, 0x14000
	ds_read_b128 v[140:143], v144
	ds_read_b128 v[154:157], v144 offset:1024
	ds_read_b128 v[158:161], v144 offset:2048
	ds_read_b128 v[162:165], v144 offset:3072
	ds_read_b128 v[166:169], v144 offset:16384
	ds_read_b128 v[170:173], v144 offset:17408
	ds_read_b128 v[174:177], v144 offset:18432
	ds_read_b128 v[194:197], v144 offset:19456
	s_add_i32 m0, s27, 0xc000
	ds_read_b128 v[198:201], v153
	ds_read_b128 v[202:205], v153 offset:1024
	ds_read_b128 v[206:209], v153 offset:2048
	ds_read_b128 v[210:213], v153 offset:3072
	ds_read_b128 v[234:237], v153 offset:4096
	ds_read_b128 v[238:241], v153 offset:5120
	ds_read_b128 v[242:245], v153 offset:6144
	ds_read_b128 v[246:249], v153 offset:7168
	global_load_lds_dwordx4 v136, s[16:17]
	s_add_i32 m0, s27, 0xe000
	s_nop 0
	global_load_lds_dwordx4 v138, s[16:17]
	s_waitcnt vmcnt(8)
	s_waitcnt lgkmcnt(0)
	s_barrier
; #define PG8_STAGE(bufoff, gbase, voff) do { _Pragma("unroll") for (int _i = 0; _i < 2; ++_i) \
;         __builtin_amdgcn_global_load_lds((const unsigned*)((const char*)(gbase) + (voff)[_i]), (LAS unsigned*)(lds + (bufoff) + ldsw + _i * 8192), 16, 0, 0); } while (0)
; #define PG8_LDA(dst, b, h) do { _Pragma("unroll") for (int m = 0; m < 4; ++m) _Pragma("unroll") for (int k = 0; k < 2; ++k) dst[m][k] = *(const LAS bf16x8*)(lds + PG8_SA(b, h) + aoff + m * 2048 + k * 1024); } while (0)
; #define PG8_MMA(ai, bj, At, Bt) do { __builtin_amdgcn_s_setprio(1); _Pragma("unroll") for (int m = 0; m < 4; ++m) _Pragma("unroll") for (int n = 0; n < 2; ++n) _Pragma("unroll") for (int k = 0; k < 2; ++k) \
;         acc[ai][bj][m][n] = __builtin_amdgcn_mfma_f32_16x16x32_bf16(Bt[n][k], At[m][k], acc[ai][bj][m][n], 0, 0, 0); __builtin_amdgcn_s_setprio(0); } while (0)
; #define PG8_WAIT_V(n) asm volatile("s_waitcnt vmcnt(" #n ")" ::: "memory")
; #define PG8_WAIT_L(n) asm volatile("s_waitcnt lgkmcnt(" #n ")" ::: "memory")
; #define PG8_BAR __builtin_amdgcn_s_barrier()
; #define PG8_SCHED __builtin_amdgcn_sched_barrier(0)
; template <class Epi, class Sched, bool ALIGN_EPI = true, bool SP2 = true>
; __device__ __forceinline__ void gemm_phase(LAS unsigned char* lds, const Gemm g, const Sched& S, const Epi& E) {
;     ...
;             PG8_WAIT_V(8); PG8_WAIT_L(0); PG8_BAR; PG8_MMA(0, 0, At, B0); PG8_MMA(0, 1, At, B1); PG8_BAR; PG8_SCHED;
;             PG8_LDA(At, 0, 1); PG8_STAGE(PG8_SB(0, 0), b2, voffB); PG8_STAGE(PG8_SB(0, 1), b2 + hstep, voffB); PG8_STAGE(PG8_SA(0, 0), a2, voffA);
;             PG8_WAIT_V(8); PG8_WAIT_L(0); PG8_BAR; PG8_MMA(1, 0, At, B0); PG8_MMA(1, 1, At, B1); PG8_BAR; PG8_SCHED;
	s_setprio 1
	s_waitcnt lgkmcnt(0)
	v_mfma_f32_16x16x32_bf16 v[126:129], v[140:143], v[198:201], v[126:129]
	v_mfma_f32_16x16x32_bf16 v[122:125], v[158:161], v[198:201], v[122:125]
	v_mfma_f32_16x16x32_bf16 v[114:117], v[140:143], v[206:209], v[114:117]
	v_mfma_f32_16x16x32_bf16 v[106:109], v[158:161], v[206:209], v[106:109]
	v_mfma_f32_16x16x32_bf16 v[98:101], v[140:143], v[234:237], v[98:101]
	v_mfma_f32_16x16x32_bf16 v[90:93], v[158:161], v[234:237], v[90:93]
	v_mfma_f32_16x16x32_bf16 v[82:85], v[140:143], v[242:245], v[82:85]
	v_mfma_f32_16x16x32_bf16 v[74:77], v[158:161], v[242:245], v[74:77]
	v_mfma_f32_16x16x32_bf16 v[126:129], v[154:157], v[202:205], v[126:129]
	v_mfma_f32_16x16x32_bf16 v[122:125], v[162:165], v[202:205], v[122:125]
	v_mfma_f32_16x16x32_bf16 v[114:117], v[154:157], v[210:213], v[114:117]
	v_mfma_f32_16x16x32_bf16 v[106:109], v[162:165], v[210:213], v[106:109]
	v_mfma_f32_16x16x32_bf16 v[98:101], v[154:157], v[238:241], v[98:101]
	v_mfma_f32_16x16x32_bf16 v[90:93], v[162:165], v[238:241], v[90:93]
	v_mfma_f32_16x16x32_bf16 v[82:85], v[154:157], v[246:249], v[82:85]
	v_mfma_f32_16x16x32_bf16 v[74:77], v[162:165], v[246:249], v[74:77]
	s_setprio 0
	s_setprio 1
	v_mfma_f32_16x16x32_bf16 v[118:121], v[166:169], v[198:201], v[118:121]
	v_mfma_f32_16x16x32_bf16 v[110:113], v[174:177], v[198:201], v[110:113]
	v_mfma_f32_16x16x32_bf16 v[102:105], v[166:169], v[206:209], v[102:105]
	v_mfma_f32_16x16x32_bf16 v[94:97], v[174:177], v[206:209], v[94:97]
	v_mfma_f32_16x16x32_bf16 v[86:89], v[166:169], v[234:237], v[86:89]
	v_mfma_f32_16x16x32_bf16 v[78:81], v[174:177], v[234:237], v[78:81]
	v_mfma_f32_16x16x32_bf16 v[70:73], v[166:169], v[242:245], v[70:73]
	v_mfma_f32_16x16x32_bf16 v[66:69], v[174:177], v[242:245], v[66:69]
	v_mfma_f32_16x16x32_bf16 v[118:121], v[170:173], v[202:205], v[118:121]
	v_mfma_f32_16x16x32_bf16 v[110:113], v[194:197], v[202:205], v[110:113]
	v_mfma_f32_16x16x32_bf16 v[102:105], v[170:173], v[210:213], v[102:105]
	v_mfma_f32_16x16x32_bf16 v[94:97], v[194:197], v[210:213], v[94:97]
	v_mfma_f32_16x16x32_bf16 v[86:89], v[170:173], v[238:241], v[86:89]
	v_mfma_f32_16x16x32_bf16 v[78:81], v[194:197], v[238:241], v[78:81]
	v_mfma_f32_16x16x32_bf16 v[70:73], v[170:173], v[246:249], v[70:73]
	v_mfma_f32_16x16x32_bf16 v[66:69], v[194:197], v[246:249], v[66:69]
	s_setprio 0
	s_barrier
	s_add_i32 s58, s58, s26
	s_mov_b32 m0, s58
	ds_read_b128 v[198:201], v153 offset:16384
	ds_read_b128 v[202:205], v153 offset:17408
	ds_read_b128 v[206:209], v153 offset:18432
	ds_read_b128 v[210:213], v153 offset:19456
	ds_read_b128 v[234:237], v153 offset:20480
	ds_read_b128 v[238:241], v153 offset:21504
	ds_read_b128 v[242:245], v153 offset:22528
	ds_read_b128 v[246:249], v153 offset:23552
	global_load_lds_dwordx4 v0, s[20:21]
	s_add_i32 m0, s58, 0x2000
	s_add_u32 s58, s20, 0x80000
	s_addc_u32 s59, s21, 0
	s_add_i32 s75, s75, s26
	global_load_lds_dwordx4 v130, s[20:21]
	s_mov_b32 m0, s75
	s_nop 0
	global_load_lds_dwordx4 v0, s[58:59]
	s_add_i32 m0, s75, 0x2000
	s_nop 0
	global_load_lds_dwordx4 v130, s[58:59]
	s_mov_b32 m0, s27
	s_nop 0
	global_load_lds_dwordx4 v134, s[22:23]
	s_mov_b32 m0, s28
	s_nop 0
	global_load_lds_dwordx4 v132, s[22:23]
	s_waitcnt vmcnt(8)
	s_waitcnt lgkmcnt(0)
	s_barrier
	s_setprio 1
	s_waitcnt lgkmcnt(0)
	v_mfma_f32_16x16x32_bf16 v[62:65], v[140:143], v[198:201], v[62:65]
	v_mfma_f32_16x16x32_bf16 v[58:61], v[158:161], v[198:201], v[58:61]
	v_mfma_f32_16x16x32_bf16 v[50:53], v[140:143], v[206:209], v[50:53]
	v_mfma_f32_16x16x32_bf16 v[42:45], v[158:161], v[206:209], v[42:45]
	v_mfma_f32_16x16x32_bf16 v[34:37], v[140:143], v[234:237], v[34:37]
	v_mfma_f32_16x16x32_bf16 v[26:29], v[158:161], v[234:237], v[26:29]
	v_mfma_f32_16x16x32_bf16 v[18:21], v[140:143], v[242:245], v[18:21]
	v_mfma_f32_16x16x32_bf16 v[10:13], v[158:161], v[242:245], v[10:13]
	v_mfma_f32_16x16x32_bf16 v[62:65], v[154:157], v[202:205], v[62:65]
	v_mfma_f32_16x16x32_bf16 v[58:61], v[162:165], v[202:205], v[58:61]
	v_mfma_f32_16x16x32_bf16 v[50:53], v[154:157], v[210:213], v[50:53]
	v_mfma_f32_16x16x32_bf16 v[42:45], v[162:165], v[210:213], v[42:45]
	v_mfma_f32_16x16x32_bf16 v[34:37], v[154:157], v[238:241], v[34:37]
	v_mfma_f32_16x16x32_bf16 v[26:29], v[162:165], v[238:241], v[26:29]
	v_mfma_f32_16x16x32_bf16 v[18:21], v[154:157], v[246:249], v[18:21]
	v_mfma_f32_16x16x32_bf16 v[10:13], v[162:165], v[246:249], v[10:13]
	s_setprio 0
	s_setprio 1
	v_mfma_f32_16x16x32_bf16 v[54:57], v[166:169], v[198:201], v[54:57]
	v_mfma_f32_16x16x32_bf16 v[46:49], v[174:177], v[198:201], v[46:49]
	v_mfma_f32_16x16x32_bf16 v[38:41], v[166:169], v[206:209], v[38:41]
	v_mfma_f32_16x16x32_bf16 v[30:33], v[174:177], v[206:209], v[30:33]
	v_mfma_f32_16x16x32_bf16 v[22:25], v[166:169], v[234:237], v[22:25]
	v_mfma_f32_16x16x32_bf16 v[14:17], v[174:177], v[234:237], v[14:17]
	v_mfma_f32_16x16x32_bf16 v[6:9], v[166:169], v[242:245], v[6:9]
	v_mfma_f32_16x16x32_bf16 v[2:5], v[174:177], v[242:245], v[2:5]
	v_mfma_f32_16x16x32_bf16 v[54:57], v[170:173], v[202:205], v[54:57]
	v_mfma_f32_16x16x32_bf16 v[46:49], v[194:197], v[202:205], v[46:49]
	v_mfma_f32_16x16x32_bf16 v[38:41], v[170:173], v[210:213], v[38:41]
	v_mfma_f32_16x16x32_bf16 v[30:33], v[194:197], v[210:213], v[30:33]
	v_mfma_f32_16x16x32_bf16 v[22:25], v[170:173], v[238:241], v[22:25]
	v_mfma_f32_16x16x32_bf16 v[14:17], v[194:197], v[238:241], v[14:17]
	v_mfma_f32_16x16x32_bf16 v[6:9], v[170:173], v[246:249], v[6:9]
	v_mfma_f32_16x16x32_bf16 v[2:5], v[194:197], v[246:249], v[2:5]
	s_setprio 0
	s_barrier
; #define PG8_STAGE(bufoff, gbase, voff) do { _Pragma("unroll") for (int _i = 0; _i < 2; ++_i) \
;         __builtin_amdgcn_global_load_lds((const unsigned*)((const char*)(gbase) + (voff)[_i]), (LAS unsigned*)(lds + (bufoff) + ldsw + _i * 8192), 16, 0, 0); } while (0)
; #define PG8_LDA(dst, b, h) do { _Pragma("unroll") for (int m = 0; m < 4; ++m) _Pragma("unroll") for (int k = 0; k < 2; ++k) dst[m][k] = *(const LAS bf16x8*)(lds + PG8_SA(b, h) + aoff + m * 2048 + k * 1024); } while (0)
; #define PG8_LDB(dst, b, h) do { _Pragma("unroll") for (int n = 0; n < 2; ++n) _Pragma("unroll") for (int k = 0; k < 2; ++k) dst[n][k] = *(const LAS bf16x8*)(lds + PG8_SB(b, h) + boff + n * 2048 + k * 1024); } while (0)
; #define PG8_MMA(ai, bj, At, Bt) do { __builtin_amdgcn_s_setprio(1); _Pragma("unroll") for (int m = 0; m < 4; ++m) _Pragma("unroll") for (int n = 0; n < 2; ++n) _Pragma("unroll") for (int k = 0; k < 2; ++k) \
;         acc[ai][bj][m][n] = __builtin_amdgcn_mfma_f32_16x16x32_bf16(Bt[n][k], At[m][k], acc[ai][bj][m][n], 0, 0, 0); __builtin_amdgcn_s_setprio(0); } while (0)
; #define PG8_WAIT_V(n) asm volatile("s_waitcnt vmcnt(" #n ")" ::: "memory")
; #define PG8_WAIT_L(n) asm volatile("s_waitcnt lgkmcnt(" #n ")" ::: "memory")
; #define PG8_BAR __builtin_amdgcn_s_barrier()
; #define PG8_SCHED __builtin_amdgcn_sched_barrier(0)
; template <class Epi, class Sched, bool ALIGN_EPI = true, bool SP2 = true>
; __device__ __forceinline__ void gemm_phase(LAS unsigned char* lds, const Gemm g, const Sched& S, const Epi& E) {
;     ...
;             PG8_LDB(B0, 1, 0); PG8_LDB(B1, 1, 1); PG8_SCHED; PG8_LDA(At, 1, 0); PG8_STAGE(PG8_SA(0, 1), a2 + hstep, voffA);
;             PG8_WAIT_V(8); PG8_WAIT_L(0); PG8_BAR; PG8_MMA(0, 0, At, B0); PG8_MMA(0, 1, At, B1); PG8_BAR; PG8_SCHED;
;             PG8_LDA(At, 1, 1); PG8_STAGE(PG8_SB(1, 0), b3, voffB); PG8_STAGE(PG8_SB(1, 1), b3 + hstep, voffB); PG8_STAGE(PG8_SA(1, 0), a3, voffA);
;             PG8_WAIT_V(8); PG8_WAIT_L(0); PG8_BAR; PG8_MMA(1, 0, At, B0); PG8_MMA(1, 1, At, B1); PG8_BAR; PG8_SCHED;
	s_add_i32 s58, 0, 0x18000
	v_add_u32_e32 v144, s58, v147
	s_add_i32 s59, 0, 0x1c000
	ds_read_b128 v[140:143], v144
	ds_read_b128 v[154:157], v144 offset:1024
	ds_read_b128 v[158:161], v144 offset:2048
	ds_read_b128 v[162:165], v144 offset:3072
	ds_read_b128 v[166:169], v144 offset:16384
	ds_read_b128 v[170:173], v144 offset:17408
	ds_read_b128 v[174:177], v144 offset:18432
	ds_read_b128 v[194:197], v144 offset:19456
	s_add_u32 s22, s22, 0x80000
	s_addc_u32 s23, s23, 0
	s_mov_b32 m0, s29
	ds_read_b128 v[198:201], v153 offset:32768
	ds_read_b128 v[202:205], v153 offset:33792
	ds_read_b128 v[206:209], v153 offset:34816
	ds_read_b128 v[210:213], v153 offset:35840
	ds_read_b128 v[234:237], v153 offset:36864
	ds_read_b128 v[238:241], v153 offset:37888
	ds_read_b128 v[242:245], v153 offset:38912
	ds_read_b128 v[246:249], v153 offset:39936
	global_load_lds_dwordx4 v134, s[22:23]
	s_mov_b32 m0, s30
	s_nop 0
	global_load_lds_dwordx4 v132, s[22:23]
	s_waitcnt vmcnt(8)
	s_waitcnt lgkmcnt(0)
	s_barrier
	s_setprio 1
	s_waitcnt lgkmcnt(0)
	v_mfma_f32_16x16x32_bf16 v[126:129], v[140:143], v[198:201], v[126:129]
	v_mfma_f32_16x16x32_bf16 v[122:125], v[158:161], v[198:201], v[122:125]
	v_mfma_f32_16x16x32_bf16 v[114:117], v[140:143], v[206:209], v[114:117]
	v_mfma_f32_16x16x32_bf16 v[106:109], v[158:161], v[206:209], v[106:109]
	v_mfma_f32_16x16x32_bf16 v[98:101], v[140:143], v[234:237], v[98:101]
	v_mfma_f32_16x16x32_bf16 v[90:93], v[158:161], v[234:237], v[90:93]
	v_mfma_f32_16x16x32_bf16 v[82:85], v[140:143], v[242:245], v[82:85]
	v_mfma_f32_16x16x32_bf16 v[74:77], v[158:161], v[242:245], v[74:77]
	v_mfma_f32_16x16x32_bf16 v[126:129], v[154:157], v[202:205], v[126:129]
	v_mfma_f32_16x16x32_bf16 v[122:125], v[162:165], v[202:205], v[122:125]
	v_mfma_f32_16x16x32_bf16 v[114:117], v[154:157], v[210:213], v[114:117]
	v_mfma_f32_16x16x32_bf16 v[106:109], v[162:165], v[210:213], v[106:109]
	v_mfma_f32_16x16x32_bf16 v[98:101], v[154:157], v[238:241], v[98:101]
	v_mfma_f32_16x16x32_bf16 v[90:93], v[162:165], v[238:241], v[90:93]
	v_mfma_f32_16x16x32_bf16 v[82:85], v[154:157], v[246:249], v[82:85]
	v_mfma_f32_16x16x32_bf16 v[74:77], v[162:165], v[246:249], v[74:77]
	s_setprio 0
	s_setprio 1
	v_mfma_f32_16x16x32_bf16 v[118:121], v[166:169], v[198:201], v[118:121]
	v_mfma_f32_16x16x32_bf16 v[110:113], v[174:177], v[198:201], v[110:113]
	v_mfma_f32_16x16x32_bf16 v[102:105], v[166:169], v[206:209], v[102:105]
	v_mfma_f32_16x16x32_bf16 v[94:97], v[174:177], v[206:209], v[94:97]
	v_mfma_f32_16x16x32_bf16 v[86:89], v[166:169], v[234:237], v[86:89]
	v_mfma_f32_16x16x32_bf16 v[78:81], v[174:177], v[234:237], v[78:81]
	v_mfma_f32_16x16x32_bf16 v[70:73], v[166:169], v[242:245], v[70:73]
	v_mfma_f32_16x16x32_bf16 v[66:69], v[174:177], v[242:245], v[66:69]
	v_mfma_f32_16x16x32_bf16 v[118:121], v[170:173], v[202:205], v[118:121]
	v_mfma_f32_16x16x32_bf16 v[110:113], v[194:197], v[202:205], v[110:113]
	v_mfma_f32_16x16x32_bf16 v[102:105], v[170:173], v[210:213], v[102:105]
	v_mfma_f32_16x16x32_bf16 v[94:97], v[194:197], v[210:213], v[94:97]
	v_mfma_f32_16x16x32_bf16 v[86:89], v[170:173], v[238:241], v[86:89]
	v_mfma_f32_16x16x32_bf16 v[78:81], v[194:197], v[238:241], v[78:81]
	v_mfma_f32_16x16x32_bf16 v[70:73], v[170:173], v[246:249], v[70:73]
	v_mfma_f32_16x16x32_bf16 v[66:69], v[194:197], v[246:249], v[66:69]
	s_setprio 0
	s_barrier
	s_add_i32 s32, s58, s26
	s_add_u32 s20, s20, s92
	s_addc_u32 s21, s21, s93
	s_mov_b32 m0, s32
	ds_read_b128 v[198:201], v153 offset:49152
	ds_read_b128 v[202:205], v153 offset:50176
	ds_read_b128 v[206:209], v153 offset:51200
	ds_read_b128 v[210:213], v153 offset:52224
	ds_read_b128 v[234:237], v153 offset:53248
	ds_read_b128 v[238:241], v153 offset:54272
	ds_read_b128 v[242:245], v153 offset:55296
	ds_read_b128 v[246:249], v153 offset:56320
	global_load_lds_dwordx4 v0, s[20:21]
	s_add_i32 m0, s32, 0x2000
	s_add_i32 s32, s59, s26
	global_load_lds_dwordx4 v130, s[20:21]
	s_add_u32 s20, s20, 0x80000
	s_addc_u32 s21, s21, 0
	s_mov_b32 m0, s32
	s_nop 0
	global_load_lds_dwordx4 v0, s[20:21]
	s_add_i32 m0, s32, 0x2000
	s_nop 0
	global_load_lds_dwordx4 v130, s[20:21]
	s_add_u32 s22, s22, 0xfff80080
	s_addc_u32 s23, s23, -1
	s_mov_b32 m0, s31
	s_nop 0
	global_load_lds_dwordx4 v134, s[22:23]
	s_mov_b32 m0, s34
	s_nop 0
	global_load_lds_dwordx4 v132, s[22:23]
	s_waitcnt vmcnt(8)
	s_waitcnt lgkmcnt(0)
	s_barrier
	s_setprio 1
	s_waitcnt lgkmcnt(0)
	v_mfma_f32_16x16x32_bf16 v[62:65], v[140:143], v[198:201], v[62:65]
	v_mfma_f32_16x16x32_bf16 v[58:61], v[158:161], v[198:201], v[58:61]
	v_mfma_f32_16x16x32_bf16 v[50:53], v[140:143], v[206:209], v[50:53]
	v_mfma_f32_16x16x32_bf16 v[42:45], v[158:161], v[206:209], v[42:45]
	v_mfma_f32_16x16x32_bf16 v[34:37], v[140:143], v[234:237], v[34:37]
	v_mfma_f32_16x16x32_bf16 v[26:29], v[158:161], v[234:237], v[26:29]
	v_mfma_f32_16x16x32_bf16 v[18:21], v[140:143], v[242:245], v[18:21]
	v_mfma_f32_16x16x32_bf16 v[10:13], v[158:161], v[242:245], v[10:13]
	v_mfma_f32_16x16x32_bf16 v[62:65], v[154:157], v[202:205], v[62:65]
	v_mfma_f32_16x16x32_bf16 v[58:61], v[162:165], v[202:205], v[58:61]
	v_mfma_f32_16x16x32_bf16 v[50:53], v[154:157], v[210:213], v[50:53]
	v_mfma_f32_16x16x32_bf16 v[42:45], v[162:165], v[210:213], v[42:45]
	v_mfma_f32_16x16x32_bf16 v[34:37], v[154:157], v[238:241], v[34:37]
	v_mfma_f32_16x16x32_bf16 v[26:29], v[162:165], v[238:241], v[26:29]
	v_mfma_f32_16x16x32_bf16 v[18:21], v[154:157], v[246:249], v[18:21]
	v_mfma_f32_16x16x32_bf16 v[10:13], v[162:165], v[246:249], v[10:13]
	s_setprio 0
	s_setprio 1
	v_mfma_f32_16x16x32_bf16 v[54:57], v[166:169], v[198:201], v[54:57]
	v_mfma_f32_16x16x32_bf16 v[46:49], v[174:177], v[198:201], v[46:49]
	v_mfma_f32_16x16x32_bf16 v[38:41], v[166:169], v[206:209], v[38:41]
	v_mfma_f32_16x16x32_bf16 v[30:33], v[174:177], v[206:209], v[30:33]
	v_mfma_f32_16x16x32_bf16 v[22:25], v[166:169], v[234:237], v[22:25]
	v_mfma_f32_16x16x32_bf16 v[14:17], v[174:177], v[234:237], v[14:17]
	v_mfma_f32_16x16x32_bf16 v[6:9], v[166:169], v[242:245], v[6:9]
	v_mfma_f32_16x16x32_bf16 v[2:5], v[174:177], v[242:245], v[2:5]
	v_mfma_f32_16x16x32_bf16 v[54:57], v[170:173], v[202:205], v[54:57]
	v_mfma_f32_16x16x32_bf16 v[46:49], v[194:197], v[202:205], v[46:49]
	v_mfma_f32_16x16x32_bf16 v[38:41], v[170:173], v[210:213], v[38:41]
	v_mfma_f32_16x16x32_bf16 v[30:33], v[194:197], v[210:213], v[30:33]
	v_mfma_f32_16x16x32_bf16 v[22:25], v[170:173], v[238:241], v[22:25]
	v_mfma_f32_16x16x32_bf16 v[14:17], v[194:197], v[238:241], v[14:17]
	v_mfma_f32_16x16x32_bf16 v[6:9], v[170:173], v[246:249], v[6:9]
	v_mfma_f32_16x16x32_bf16 v[2:5], v[194:197], v[246:249], v[2:5]
	s_setprio 0
	s_barrier
	s_add_i32 s74, s74, 2
	s_add_u32 s16, s16, 0x100
	s_addc_u32 s17, s17, 0
	s_add_u32 s72, s72, 0x100
	s_addc_u32 s73, s73, 0
	s_cmp_gt_u32 s74, 29
	s_cbranch_scc0 .LBB0_306
	s_and_b64 vcc, exec, s[4:5]
	s_cbranch_vccz .LBB0_309
	s_barrier

;     __device__ bool next(int i, Unit& u) const { if (!so.next(i >> 1, u)) return false; u.kind = i & 1; return true; }
; #define PG8_STAGE(bufoff, gbase, voff) do { _Pragma("unroll") for (int _i = 0; _i < 2; ++_i) \
;         __builtin_amdgcn_global_load_lds((const unsigned*)((const char*)(gbase) + (voff)[_i]), (LAS unsigned*)(lds + (bufoff) + ldsw + _i * 8192), 16, 0, 0); } while (0)
; #define PG8_LDA(dst, b, h) do { _Pragma("unroll") for (int m = 0; m < 4; ++m) _Pragma("unroll") for (int k = 0; k < 2; ++k) dst[m][k] = *(const LAS bf16x8*)(lds + PG8_SA(b, h) + aoff + m * 2048 + k * 1024); } while (0)
; #define PG8_LDB(dst, b, h) do { _Pragma("unroll") for (int n = 0; n < 2; ++n) _Pragma("unroll") for (int k = 0; k < 2; ++k) dst[n][k] = *(const LAS bf16x8*)(lds + PG8_SB(b, h) + boff + n * 2048 + k * 1024); } while (0)
; #define PG8_WAIT_V(n) asm volatile("s_waitcnt vmcnt(" #n ")" ::: "memory")
; #define PG8_WAIT_L(n) asm volatile("s_waitcnt lgkmcnt(" #n ")" ::: "memory")
; #define PG8_BAR __builtin_amdgcn_s_barrier()
; template <class Epi, class Sched, bool ALIGN_EPI = true, bool SP2 = true>
; __device__ __forceinline__ void gemm_phase(LAS unsigned char* lds, const Gemm g, const Sched& S, const Epi& E) {
;     ...
;         const bool has_next = S.next(ui + 1, nxt);
;         const char* nA = has_next ? (const char*)(nxt.kind ? g.A1 : g.A0) + (size_t)nxt.pm * tstep : cA; const char* nB = has_next ? (const char*)(nxt.kind ? g.B1 : g.B0) + (size_t)nxt.pn * tstep : cB;
;         for (int t = 0; t < nt; t += 2) {
;             const bool last = (t == nt - 2);
;             const char* a1 = cA + (size_t)(t + 1) * kstep;
;             const char* a2 = last ? nA : cA + (size_t)(t + 2) * kstep; const char* b2 = last ? nB : cB + (size_t)(t + 2) * kstep;
;             const char* a3 = a2 + kstep; const char* b3 = b2 + kstep;
;             if constexpr (SP2) {
;             PG8_LDB(B0, 0, 0); PG8_LDB(B1, 0, 1); PG8_SCHED; PG8_LDA(At, 0, 0); PG8_STAGE(PG8_SA(1, 1), a1 + hstep, voffA);
;             PG8_WAIT_V(8); PG8_WAIT_L(0); PG8_BAR; PG8_MMA(0, 0, At, B0); PG8_MMA(0, 1, At, B1); PG8_BAR; PG8_SCHED;
;             PG8_LDA(At, 0, 1); PG8_STAGE(PG8_SB(0, 0), b2, voffB); PG8_STAGE(PG8_SB(0, 1), b2 + hstep, voffB); PG8_STAGE(PG8_SA(0, 0), a2, voffA);
;             PG8_WAIT_V(8); PG8_WAIT_L(0); PG8_BAR; PG8_MMA(1, 0, At, B0); PG8_MMA(1, 1, At, B1); PG8_BAR; PG8_SCHED;
.LBB0_870:
	s_ashr_i32 s17, s16, 31
	s_lshl_b64 s[18:19], s[16:17], 20
	s_add_u32 s18, s88, s18
	s_addc_u32 s19, s89, s19
	s_and_b64 s[20:21], s[8:9], exec
	s_cselect_b32 s17, s19, s5
	s_cselect_b32 s70, s18, s4
	s_ashr_i32 s15, s14, 31
	s_lshl_b64 s[20:21], s[14:15], 20
	s_add_u32 s20, s24, s20
	s_addc_u32 s21, s25, s21
	s_and_b64 s[22:23], s[8:9], exec
	s_cselect_b32 s15, s21, s7
	s_cselect_b32 s71, s20, s6
	s_add_u32 s4, s4, 0x80080
	s_addc_u32 s5, s5, 0
	s_add_u32 s72, s6, 0x100
	s_addc_u32 s73, s7, 0
	s_mov_b32 s74, -2
	s_add_u32 s6, s4, 0xfff80080
	s_addc_u32 s7, s5, -1
	s_add_i32 s58, 0, 0x10000
	s_cmp_eq_u32 s74, 28
	s_cselect_b32 s23, s17, s7
	s_cselect_b32 s22, s70, s6
	v_add_u32_e32 v148, s58, v153
	s_cselect_b32 s7, s15, s73
	s_cselect_b32 s6, s71, s72
	s_add_i32 s75, 0, 0x14000
	ds_read_b128 v[140:143], v148
	ds_read_b128 v[144:147], v148 offset:1024
	ds_read_b128 v[160:163], v148 offset:2048
	ds_read_b128 v[164:167], v148 offset:3072
	ds_read_b128 v[168:171], v148 offset:16384
	ds_read_b128 v[172:175], v148 offset:17408
	ds_read_b128 v[176:179], v148 offset:18432
	ds_read_b128 v[194:197], v148 offset:19456
	s_add_i32 m0, s27, 0xc000
	ds_read_b128 v[198:201], v159
	ds_read_b128 v[202:205], v159 offset:1024
	ds_read_b128 v[206:209], v159 offset:2048
	ds_read_b128 v[210:213], v159 offset:3072
	ds_read_b128 v[234:237], v159 offset:4096
	ds_read_b128 v[238:241], v159 offset:5120
	ds_read_b128 v[242:245], v159 offset:6144
	ds_read_b128 v[246:249], v159 offset:7168
	global_load_lds_dwordx4 v136, s[4:5]
	s_add_i32 m0, s27, 0xe000
	s_nop 0
	global_load_lds_dwordx4 v138, s[4:5]
	s_waitcnt vmcnt(8)
	s_waitcnt lgkmcnt(0)
	s_barrier
	s_setprio 1
	s_waitcnt lgkmcnt(0)
	v_mfma_f32_16x16x32_bf16 v[126:129], v[140:143], v[198:201], 0
	v_mfma_f32_16x16x32_bf16 v[118:121], v[160:163], v[198:201], 0
	v_mfma_f32_16x16x32_bf16 v[110:113], v[140:143], v[206:209], 0
	v_mfma_f32_16x16x32_bf16 v[102:105], v[160:163], v[206:209], 0
	v_mfma_f32_16x16x32_bf16 v[94:97], v[140:143], v[234:237], 0
	v_mfma_f32_16x16x32_bf16 v[86:89], v[160:163], v[234:237], 0
	v_mfma_f32_16x16x32_bf16 v[78:81], v[140:143], v[242:245], 0
	v_mfma_f32_16x16x32_bf16 v[70:73], v[160:163], v[242:245], 0
	v_mfma_f32_16x16x32_bf16 v[126:129], v[144:147], v[202:205], v[126:129]
	v_mfma_f32_16x16x32_bf16 v[118:121], v[164:167], v[202:205], v[118:121]
	v_mfma_f32_16x16x32_bf16 v[110:113], v[144:147], v[210:213], v[110:113]
	v_mfma_f32_16x16x32_bf16 v[102:105], v[164:167], v[210:213], v[102:105]
	v_mfma_f32_16x16x32_bf16 v[94:97], v[144:147], v[238:241], v[94:97]
	v_mfma_f32_16x16x32_bf16 v[86:89], v[164:167], v[238:241], v[86:89]
	v_mfma_f32_16x16x32_bf16 v[78:81], v[144:147], v[246:249], v[78:81]
	v_mfma_f32_16x16x32_bf16 v[70:73], v[164:167], v[246:249], v[70:73]
	s_setprio 0
	s_setprio 1
	v_mfma_f32_16x16x32_bf16 v[122:125], v[168:171], v[198:201], 0
	v_mfma_f32_16x16x32_bf16 v[114:117], v[176:179], v[198:201], 0
	v_mfma_f32_16x16x32_bf16 v[106:109], v[168:171], v[206:209], 0
	v_mfma_f32_16x16x32_bf16 v[98:101], v[176:179], v[206:209], 0
	v_mfma_f32_16x16x32_bf16 v[90:93], v[168:171], v[234:237], 0
	v_mfma_f32_16x16x32_bf16 v[82:85], v[176:179], v[234:237], 0
	v_mfma_f32_16x16x32_bf16 v[74:77], v[168:171], v[242:245], 0
	v_mfma_f32_16x16x32_bf16 v[66:69], v[176:179], v[242:245], 0
	v_mfma_f32_16x16x32_bf16 v[122:125], v[172:175], v[202:205], v[122:125]
	v_mfma_f32_16x16x32_bf16 v[114:117], v[194:197], v[202:205], v[114:117]
	v_mfma_f32_16x16x32_bf16 v[106:109], v[172:175], v[210:213], v[106:109]
	v_mfma_f32_16x16x32_bf16 v[98:101], v[194:197], v[210:213], v[98:101]
	v_mfma_f32_16x16x32_bf16 v[90:93], v[172:175], v[238:241], v[90:93]
	v_mfma_f32_16x16x32_bf16 v[82:85], v[194:197], v[238:241], v[82:85]
	v_mfma_f32_16x16x32_bf16 v[74:77], v[172:175], v[246:249], v[74:77]
	v_mfma_f32_16x16x32_bf16 v[66:69], v[194:197], v[246:249], v[66:69]
	s_setprio 0
	s_barrier
	s_add_i32 s58, s58, s26
	s_mov_b32 m0, s58
	ds_read_b128 v[198:201], v159 offset:16384
	ds_read_b128 v[202:205], v159 offset:17408
	ds_read_b128 v[206:209], v159 offset:18432
	ds_read_b128 v[210:213], v159 offset:19456
	ds_read_b128 v[234:237], v159 offset:20480
	ds_read_b128 v[238:241], v159 offset:21504
	ds_read_b128 v[242:245], v159 offset:22528
	ds_read_b128 v[246:249], v159 offset:23552
	global_load_lds_dwordx4 v0, s[6:7]
	s_add_i32 m0, s58, 0x2000
	s_add_u32 s58, s6, 0x80000
	s_addc_u32 s59, s7, 0
	s_add_i32 s75, s75, s26
	global_load_lds_dwordx4 v130, s[6:7]
	s_mov_b32 m0, s75
	s_nop 0
	global_load_lds_dwordx4 v0, s[58:59]
	s_add_i32 m0, s75, 0x2000
	s_nop 0
	global_load_lds_dwordx4 v130, s[58:59]
	s_mov_b32 m0, s27
	s_nop 0
	global_load_lds_dwordx4 v134, s[22:23]
	s_mov_b32 m0, s28
	s_nop 0
	global_load_lds_dwordx4 v132, s[22:23]
	s_waitcnt vmcnt(8)
	s_waitcnt lgkmcnt(0)
	s_barrier
; #define PG8_STAGE(bufoff, gbase, voff) do { _Pragma("unroll") for (int _i = 0; _i < 2; ++_i) \
;         __builtin_amdgcn_global_load_lds((const unsigned*)((const char*)(gbase) + (voff)[_i]), (LAS unsigned*)(lds + (bufoff) + ldsw + _i * 8192), 16, 0, 0); } while (0)
; #define PG8_LDA(dst, b, h) do { _Pragma("unroll") for (int m = 0; m < 4; ++m) _Pragma("unroll") for (int k = 0; k < 2; ++k) dst[m][k] = *(const LAS bf16x8*)(lds + PG8_SA(b, h) + aoff + m * 2048 + k * 1024); } while (0)
; #define PG8_LDB(dst, b, h) do { _Pragma("unroll") for (int n = 0; n < 2; ++n) _Pragma("unroll") for (int k = 0; k < 2; ++k) dst[n][k] = *(const LAS bf16x8*)(lds + PG8_SB(b, h) + boff + n * 2048 + k * 1024); } while (0)
; #define PG8_MMA(ai, bj, At, Bt) do { __builtin_amdgcn_s_setprio(1); _Pragma("unroll") for (int m = 0; m < 4; ++m) _Pragma("unroll") for (int n = 0; n < 2; ++n) _Pragma("unroll") for (int k = 0; k < 2; ++k) \
;         acc[ai][bj][m][n] = __builtin_amdgcn_mfma_f32_16x16x32_bf16(Bt[n][k], At[m][k], acc[ai][bj][m][n], 0, 0, 0); __builtin_amdgcn_s_setprio(0); } while (0)
; #define PG8_WAIT_V(n) asm volatile("s_waitcnt vmcnt(" #n ")" ::: "memory")
; #define PG8_WAIT_L(n) asm volatile("s_waitcnt lgkmcnt(" #n ")" ::: "memory")
; #define PG8_BAR __builtin_amdgcn_s_barrier()
; #define PG8_SCHED __builtin_amdgcn_sched_barrier(0)
; template <class Epi, class Sched, bool ALIGN_EPI = true, bool SP2 = true>
; __device__ __forceinline__ void gemm_phase(LAS unsigned char* lds, const Gemm g, const Sched& S, const Epi& E) {
;     ...
;             PG8_WAIT_V(8); PG8_WAIT_L(0); PG8_BAR; PG8_MMA(1, 0, At, B0); PG8_MMA(1, 1, At, B1); PG8_BAR; PG8_SCHED;
;             PG8_LDB(B0, 1, 0); PG8_LDB(B1, 1, 1); PG8_SCHED; PG8_LDA(At, 1, 0); PG8_STAGE(PG8_SA(0, 1), a2 + hstep, voffA);
;             PG8_WAIT_V(8); PG8_WAIT_L(0); PG8_BAR; PG8_MMA(0, 0, At, B0); PG8_MMA(0, 1, At, B1); PG8_BAR; PG8_SCHED;
;             PG8_LDA(At, 1, 1); PG8_STAGE(PG8_SB(1, 0), b3, voffB); PG8_STAGE(PG8_SB(1, 1), b3 + hstep, voffB); PG8_STAGE(PG8_SA(1, 0), a3, voffA);
	s_setprio 1
	s_waitcnt lgkmcnt(0)
	v_mfma_f32_16x16x32_bf16 v[62:65], v[140:143], v[198:201], 0
	v_mfma_f32_16x16x32_bf16 v[54:57], v[160:163], v[198:201], 0
	v_mfma_f32_16x16x32_bf16 v[46:49], v[140:143], v[206:209], 0
	v_mfma_f32_16x16x32_bf16 v[38:41], v[160:163], v[206:209], 0
	v_mfma_f32_16x16x32_bf16 v[30:33], v[140:143], v[234:237], 0
	v_mfma_f32_16x16x32_bf16 v[22:25], v[160:163], v[234:237], 0
	v_mfma_f32_16x16x32_bf16 v[14:17], v[140:143], v[242:245], 0
	v_mfma_f32_16x16x32_bf16 v[6:9], v[160:163], v[242:245], 0
	v_mfma_f32_16x16x32_bf16 v[62:65], v[144:147], v[202:205], v[62:65]
	v_mfma_f32_16x16x32_bf16 v[54:57], v[164:167], v[202:205], v[54:57]
	v_mfma_f32_16x16x32_bf16 v[46:49], v[144:147], v[210:213], v[46:49]
	v_mfma_f32_16x16x32_bf16 v[38:41], v[164:167], v[210:213], v[38:41]
	v_mfma_f32_16x16x32_bf16 v[30:33], v[144:147], v[238:241], v[30:33]
	v_mfma_f32_16x16x32_bf16 v[22:25], v[164:167], v[238:241], v[22:25]
	v_mfma_f32_16x16x32_bf16 v[14:17], v[144:147], v[246:249], v[14:17]
	v_mfma_f32_16x16x32_bf16 v[6:9], v[164:167], v[246:249], v[6:9]
	s_setprio 0
	s_setprio 1
	v_mfma_f32_16x16x32_bf16 v[58:61], v[168:171], v[198:201], 0
	v_mfma_f32_16x16x32_bf16 v[50:53], v[176:179], v[198:201], 0
	v_mfma_f32_16x16x32_bf16 v[42:45], v[168:171], v[206:209], 0
	v_mfma_f32_16x16x32_bf16 v[34:37], v[176:179], v[206:209], 0
	v_mfma_f32_16x16x32_bf16 v[26:29], v[168:171], v[234:237], 0
	v_mfma_f32_16x16x32_bf16 v[18:21], v[176:179], v[234:237], 0
	v_mfma_f32_16x16x32_bf16 v[10:13], v[168:171], v[242:245], 0
	v_mfma_f32_16x16x32_bf16 v[2:5], v[176:179], v[242:245], 0
	v_mfma_f32_16x16x32_bf16 v[58:61], v[172:175], v[202:205], v[58:61]
	v_mfma_f32_16x16x32_bf16 v[50:53], v[194:197], v[202:205], v[50:53]
	v_mfma_f32_16x16x32_bf16 v[42:45], v[172:175], v[210:213], v[42:45]
	v_mfma_f32_16x16x32_bf16 v[34:37], v[194:197], v[210:213], v[34:37]
	v_mfma_f32_16x16x32_bf16 v[26:29], v[172:175], v[238:241], v[26:29]
	v_mfma_f32_16x16x32_bf16 v[18:21], v[194:197], v[238:241], v[18:21]
	v_mfma_f32_16x16x32_bf16 v[10:13], v[172:175], v[246:249], v[10:13]
	v_mfma_f32_16x16x32_bf16 v[2:5], v[194:197], v[246:249], v[2:5]
	s_setprio 0
	s_barrier
	s_add_i32 s58, 0, 0x18000
	v_add_u32_e32 v150, s58, v153
	s_add_i32 s59, 0, 0x1c000
	ds_read_b128 v[140:143], v150
	ds_read_b128 v[144:147], v150 offset:1024
	ds_read_b128 v[160:163], v150 offset:2048
	ds_read_b128 v[164:167], v150 offset:3072
	ds_read_b128 v[168:171], v150 offset:16384
	ds_read_b128 v[172:175], v150 offset:17408
	ds_read_b128 v[176:179], v150 offset:18432
	ds_read_b128 v[194:197], v150 offset:19456
	s_add_u32 s22, s22, 0x80000
	s_addc_u32 s23, s23, 0
	s_mov_b32 m0, s29
	ds_read_b128 v[198:201], v159 offset:32768
	ds_read_b128 v[202:205], v159 offset:33792
	ds_read_b128 v[206:209], v159 offset:34816
	ds_read_b128 v[210:213], v159 offset:35840
	ds_read_b128 v[234:237], v159 offset:36864
	ds_read_b128 v[238:241], v159 offset:37888
	ds_read_b128 v[242:245], v159 offset:38912
	ds_read_b128 v[246:249], v159 offset:39936
	global_load_lds_dwordx4 v134, s[22:23]
	s_mov_b32 m0, s30
	s_nop 0
	global_load_lds_dwordx4 v132, s[22:23]
	s_waitcnt vmcnt(8)
	s_waitcnt lgkmcnt(0)
	s_barrier
	s_setprio 1
	s_waitcnt lgkmcnt(0)
	v_mfma_f32_16x16x32_bf16 v[126:129], v[140:143], v[198:201], v[126:129]
	v_mfma_f32_16x16x32_bf16 v[118:121], v[160:163], v[198:201], v[118:121]
	v_mfma_f32_16x16x32_bf16 v[110:113], v[140:143], v[206:209], v[110:113]
	v_mfma_f32_16x16x32_bf16 v[102:105], v[160:163], v[206:209], v[102:105]
	v_mfma_f32_16x16x32_bf16 v[94:97], v[140:143], v[234:237], v[94:97]
	v_mfma_f32_16x16x32_bf16 v[86:89], v[160:163], v[234:237], v[86:89]
	v_mfma_f32_16x16x32_bf16 v[78:81], v[140:143], v[242:245], v[78:81]
	v_mfma_f32_16x16x32_bf16 v[70:73], v[160:163], v[242:245], v[70:73]
	v_mfma_f32_16x16x32_bf16 v[126:129], v[144:147], v[202:205], v[126:129]
	v_mfma_f32_16x16x32_bf16 v[118:121], v[164:167], v[202:205], v[118:121]
	v_mfma_f32_16x16x32_bf16 v[110:113], v[144:147], v[210:213], v[110:113]
	v_mfma_f32_16x16x32_bf16 v[102:105], v[164:167], v[210:213], v[102:105]
	v_mfma_f32_16x16x32_bf16 v[94:97], v[144:147], v[238:241], v[94:97]
	v_mfma_f32_16x16x32_bf16 v[86:89], v[164:167], v[238:241], v[86:89]
	v_mfma_f32_16x16x32_bf16 v[78:81], v[144:147], v[246:249], v[78:81]
	v_mfma_f32_16x16x32_bf16 v[70:73], v[164:167], v[246:249], v[70:73]
	s_setprio 0
	s_setprio 1
	v_mfma_f32_16x16x32_bf16 v[122:125], v[168:171], v[198:201], v[122:125]
	v_mfma_f32_16x16x32_bf16 v[114:117], v[176:179], v[198:201], v[114:117]
	v_mfma_f32_16x16x32_bf16 v[106:109], v[168:171], v[206:209], v[106:109]
	v_mfma_f32_16x16x32_bf16 v[98:101], v[176:179], v[206:209], v[98:101]
	v_mfma_f32_16x16x32_bf16 v[90:93], v[168:171], v[234:237], v[90:93]
	v_mfma_f32_16x16x32_bf16 v[82:85], v[176:179], v[234:237], v[82:85]
	v_mfma_f32_16x16x32_bf16 v[74:77], v[168:171], v[242:245], v[74:77]
	v_mfma_f32_16x16x32_bf16 v[66:69], v[176:179], v[242:245], v[66:69]
	v_mfma_f32_16x16x32_bf16 v[122:125], v[172:175], v[202:205], v[122:125]
	v_mfma_f32_16x16x32_bf16 v[114:117], v[194:197], v[202:205], v[114:117]
	v_mfma_f32_16x16x32_bf16 v[106:109], v[172:175], v[210:213], v[106:109]
	v_mfma_f32_16x16x32_bf16 v[98:101], v[194:197], v[210:213], v[98:101]
	v_mfma_f32_16x16x32_bf16 v[90:93], v[172:175], v[238:241], v[90:93]
	v_mfma_f32_16x16x32_bf16 v[82:85], v[194:197], v[238:241], v[82:85]
	v_mfma_f32_16x16x32_bf16 v[74:77], v[172:175], v[246:249], v[74:77]
	v_mfma_f32_16x16x32_bf16 v[66:69], v[194:197], v[246:249], v[66:69]
	s_setprio 0
	s_barrier
; #define PG8_STAGE(bufoff, gbase, voff) do { _Pragma("unroll") for (int _i = 0; _i < 2; ++_i) \
;         __builtin_amdgcn_global_load_lds((const unsigned*)((const char*)(gbase) + (voff)[_i]), (LAS unsigned*)(lds + (bufoff) + ldsw + _i * 8192), 16, 0, 0); } while (0)
; #define PG8_LDA(dst, b, h) do { _Pragma("unroll") for (int m = 0; m < 4; ++m) _Pragma("unroll") for (int k = 0; k < 2; ++k) dst[m][k] = *(const LAS bf16x8*)(lds + PG8_SA(b, h) + aoff + m * 2048 + k * 1024); } while (0)
; #define PG8_LDB(dst, b, h) do { _Pragma("unroll") for (int n = 0; n < 2; ++n) _Pragma("unroll") for (int k = 0; k < 2; ++k) dst[n][k] = *(const LAS bf16x8*)(lds + PG8_SB(b, h) + boff + n * 2048 + k * 1024); } while (0)
; #define PG8_WAIT_V(n) asm volatile("s_waitcnt vmcnt(" #n ")" ::: "memory")
; #define PG8_BAR __builtin_amdgcn_s_barrier()
; template <class Epi, class Sched, bool ALIGN_EPI = true, bool SP2 = true>
; __device__ __forceinline__ void gemm_phase(LAS unsigned char* lds, const Gemm g, const Sched& S, const Epi& E) {
;     ...
;             const bool last = (t == nt - 2);
;             const char* a1 = cA + (size_t)(t + 1) * kstep;
;             const char* a2 = last ? nA : cA + (size_t)(t + 2) * kstep; const char* b2 = last ? nB : cB + (size_t)(t + 2) * kstep;
;             const char* a3 = a2 + kstep; const char* b3 = b2 + kstep;
;             if constexpr (SP2) {
;             PG8_LDB(B0, 0, 0); PG8_LDB(B1, 0, 1); PG8_SCHED; PG8_LDA(At, 0, 0); PG8_STAGE(PG8_SA(1, 1), a1 + hstep, voffA);
;             PG8_WAIT_V(8); PG8_WAIT_L(0); PG8_BAR; PG8_MMA(0, 0, At, B0); PG8_MMA(0, 1, At, B1); PG8_BAR; PG8_SCHED;
;             PG8_LDA(At, 0, 1); PG8_STAGE(PG8_SB(0, 0), b2, voffB); PG8_STAGE(PG8_SB(0, 1), b2 + hstep, voffB); PG8_STAGE(PG8_SA(0, 0), a2, voffA);
;             PG8_WAIT_V(8); PG8_WAIT_L(0); PG8_BAR; PG8_MMA(1, 0, At, B0); PG8_MMA(1, 1, At, B1); PG8_BAR; PG8_SCHED;
;             PG8_LDB(B0, 1, 0); PG8_LDB(B1, 1, 1); PG8_SCHED; PG8_LDA(At, 1, 0); PG8_STAGE(PG8_SA(0, 1), a2 + hstep, voffA);
;             PG8_WAIT_V(8); PG8_WAIT_L(0); PG8_BAR; PG8_MMA(0, 0, At, B0); PG8_MMA(0, 1, At, B1); PG8_BAR; PG8_SCHED;
;             PG8_LDA(At, 1, 1); PG8_STAGE(PG8_SB(1, 0), b3, voffB); PG8_STAGE(PG8_SB(1, 1), b3 + hstep, voffB); PG8_STAGE(PG8_SA(1, 0), a3, voffA);
;             PG8_WAIT_V(8); PG8_WAIT_L(0); PG8_BAR; PG8_MMA(1, 0, At, B0); PG8_MMA(1, 1, At, B1); PG8_BAR; PG8_SCHED;
	s_add_i32 s32, s58, s26
	s_add_u32 s6, s6, s92
	s_addc_u32 s7, s7, s93
	s_mov_b32 m0, s32
	ds_read_b128 v[198:201], v159 offset:49152
	ds_read_b128 v[202:205], v159 offset:50176
	ds_read_b128 v[206:209], v159 offset:51200
	ds_read_b128 v[210:213], v159 offset:52224
	ds_read_b128 v[234:237], v159 offset:53248
	ds_read_b128 v[238:241], v159 offset:54272
	ds_read_b128 v[242:245], v159 offset:55296
	ds_read_b128 v[246:249], v159 offset:56320
	global_load_lds_dwordx4 v0, s[6:7]
	s_add_i32 m0, s32, 0x2000
	s_add_i32 s32, s59, s26
	global_load_lds_dwordx4 v130, s[6:7]
	s_add_u32 s6, s6, 0x80000
	s_addc_u32 s7, s7, 0
	s_mov_b32 m0, s32
	s_nop 0
	global_load_lds_dwordx4 v0, s[6:7]
	s_add_i32 m0, s32, 0x2000
	s_nop 0
	global_load_lds_dwordx4 v130, s[6:7]
	s_add_u32 s22, s22, 0xfff80080
	s_addc_u32 s23, s23, -1
	s_mov_b32 m0, s31
	s_nop 0
	global_load_lds_dwordx4 v134, s[22:23]
	s_mov_b32 m0, s34
	s_nop 0
	global_load_lds_dwordx4 v132, s[22:23]
	s_waitcnt vmcnt(8)
	s_waitcnt lgkmcnt(0)
	s_barrier
	s_setprio 1
	s_waitcnt lgkmcnt(0)
	v_mfma_f32_16x16x32_bf16 v[62:65], v[140:143], v[198:201], v[62:65]
	v_mfma_f32_16x16x32_bf16 v[54:57], v[160:163], v[198:201], v[54:57]
	v_mfma_f32_16x16x32_bf16 v[46:49], v[140:143], v[206:209], v[46:49]
	v_mfma_f32_16x16x32_bf16 v[38:41], v[160:163], v[206:209], v[38:41]
	v_mfma_f32_16x16x32_bf16 v[30:33], v[140:143], v[234:237], v[30:33]
	v_mfma_f32_16x16x32_bf16 v[22:25], v[160:163], v[234:237], v[22:25]
	v_mfma_f32_16x16x32_bf16 v[14:17], v[140:143], v[242:245], v[14:17]
	v_mfma_f32_16x16x32_bf16 v[6:9], v[160:163], v[242:245], v[6:9]
	v_mfma_f32_16x16x32_bf16 v[62:65], v[144:147], v[202:205], v[62:65]
	v_mfma_f32_16x16x32_bf16 v[54:57], v[164:167], v[202:205], v[54:57]
	v_mfma_f32_16x16x32_bf16 v[46:49], v[144:147], v[210:213], v[46:49]
	v_mfma_f32_16x16x32_bf16 v[38:41], v[164:167], v[210:213], v[38:41]
	v_mfma_f32_16x16x32_bf16 v[30:33], v[144:147], v[238:241], v[30:33]
	v_mfma_f32_16x16x32_bf16 v[22:25], v[164:167], v[238:241], v[22:25]
	v_mfma_f32_16x16x32_bf16 v[14:17], v[144:147], v[246:249], v[14:17]
	v_mfma_f32_16x16x32_bf16 v[6:9], v[164:167], v[246:249], v[6:9]
	s_setprio 0
	s_setprio 1
	v_mfma_f32_16x16x32_bf16 v[58:61], v[168:171], v[198:201], v[58:61]
	v_mfma_f32_16x16x32_bf16 v[50:53], v[176:179], v[198:201], v[50:53]
	v_mfma_f32_16x16x32_bf16 v[42:45], v[168:171], v[206:209], v[42:45]
	v_mfma_f32_16x16x32_bf16 v[34:37], v[176:179], v[206:209], v[34:37]
	v_mfma_f32_16x16x32_bf16 v[26:29], v[168:171], v[234:237], v[26:29]
	v_mfma_f32_16x16x32_bf16 v[18:21], v[176:179], v[234:237], v[18:21]
	v_mfma_f32_16x16x32_bf16 v[10:13], v[168:171], v[242:245], v[10:13]
	v_mfma_f32_16x16x32_bf16 v[2:5], v[176:179], v[242:245], v[2:5]
	v_mfma_f32_16x16x32_bf16 v[58:61], v[172:175], v[202:205], v[58:61]
	v_mfma_f32_16x16x32_bf16 v[50:53], v[194:197], v[202:205], v[50:53]
	v_mfma_f32_16x16x32_bf16 v[42:45], v[172:175], v[210:213], v[42:45]
	v_mfma_f32_16x16x32_bf16 v[34:37], v[194:197], v[210:213], v[34:37]
	v_mfma_f32_16x16x32_bf16 v[26:29], v[172:175], v[238:241], v[26:29]
	v_mfma_f32_16x16x32_bf16 v[18:21], v[194:197], v[238:241], v[18:21]
	v_mfma_f32_16x16x32_bf16 v[10:13], v[172:175], v[246:249], v[10:13]
	v_mfma_f32_16x16x32_bf16 v[2:5], v[194:197], v[246:249], v[2:5]
	s_setprio 0
	s_barrier
	s_add_i32 s74, s74, 2
	s_add_u32 s4, s4, 0x100
	s_addc_u32 s5, s5, 0
	s_add_u32 s72, s72, 0x100
	s_addc_u32 s73, s73, 0
	s_cmp_gt_u32 s74, 29
.LBB0_871:
	s_add_u32 s6, s4, 0xfff80080
	s_addc_u32 s7, s5, -1
	s_add_i32 s58, 0, 0x10000
	s_cmp_eq_u32 s74, 28
	s_cselect_b32 s23, s17, s7
	s_cselect_b32 s22, s70, s6
	v_add_u32_e32 v148, s58, v153
	s_cselect_b32 s7, s15, s73
	s_cselect_b32 s6, s71, s72
	s_add_i32 s75, 0, 0x14000
	ds_read_b128 v[140:143], v148
	ds_read_b128 v[144:147], v148 offset:1024
	ds_read_b128 v[160:163], v148 offset:2048
	ds_read_b128 v[164:167], v148 offset:3072
	ds_read_b128 v[168:171], v148 offset:16384
	ds_read_b128 v[172:175], v148 offset:17408
	ds_read_b128 v[176:179], v148 offset:18432
	ds_read_b128 v[194:197], v148 offset:19456
	s_add_i32 m0, s27, 0xc000
	ds_read_b128 v[198:201], v159
	ds_read_b128 v[202:205], v159 offset:1024
	ds_read_b128 v[206:209], v159 offset:2048
	ds_read_b128 v[210:213], v159 offset:3072
	ds_read_b128 v[234:237], v159 offset:4096
	ds_read_b128 v[238:241], v159 offset:5120
	ds_read_b128 v[242:245], v159 offset:6144
	ds_read_b128 v[246:249], v159 offset:7168
	global_load_lds_dwordx4 v136, s[4:5]
	s_add_i32 m0, s27, 0xe000
	s_nop 0
	global_load_lds_dwordx4 v138, s[4:5]
	s_waitcnt vmcnt(8)
	s_waitcnt lgkmcnt(0)
	s_barrier
; #define PG8_STAGE(bufoff, gbase, voff) do { _Pragma("unroll") for (int _i = 0; _i < 2; ++_i) \
;         __builtin_amdgcn_global_load_lds((const unsigned*)((const char*)(gbase) + (voff)[_i]), (LAS unsigned*)(lds + (bufoff) + ldsw + _i * 8192), 16, 0, 0); } while (0)
; #define PG8_LDA(dst, b, h) do { _Pragma("unroll") for (int m = 0; m < 4; ++m) _Pragma("unroll") for (int k = 0; k < 2; ++k) dst[m][k] = *(const LAS bf16x8*)(lds + PG8_SA(b, h) + aoff + m * 2048 + k * 1024); } while (0)
; #define PG8_MMA(ai, bj, At, Bt) do { __builtin_amdgcn_s_setprio(1); _Pragma("unroll") for (int m = 0; m < 4; ++m) _Pragma("unroll") for (int n = 0; n < 2; ++n) _Pragma("unroll") for (int k = 0; k < 2; ++k) \
;         acc[ai][bj][m][n] = __builtin_amdgcn_mfma_f32_16x16x32_bf16(Bt[n][k], At[m][k], acc[ai][bj][m][n], 0, 0, 0); __builtin_amdgcn_s_setprio(0); } while (0)
; #define PG8_WAIT_V(n) asm volatile("s_waitcnt vmcnt(" #n ")" ::: "memory")
; #define PG8_WAIT_L(n) asm volatile("s_waitcnt lgkmcnt(" #n ")" ::: "memory")
; #define PG8_BAR __builtin_amdgcn_s_barrier()
; #define PG8_SCHED __builtin_amdgcn_sched_barrier(0)
; template <class Epi, class Sched, bool ALIGN_EPI = true, bool SP2 = true>
; __device__ __forceinline__ void gemm_phase(LAS unsigned char* lds, const Gemm g, const Sched& S, const Epi& E) {
;     ...
;             PG8_WAIT_V(8); PG8_WAIT_L(0); PG8_BAR; PG8_MMA(0, 0, At, B0); PG8_MMA(0, 1, At, B1); PG8_BAR; PG8_SCHED;
;             PG8_LDA(At, 0, 1); PG8_STAGE(PG8_SB(0, 0), b2, voffB); PG8_STAGE(PG8_SB(0, 1), b2 + hstep, voffB); PG8_STAGE(PG8_SA(0, 0), a2, voffA);
;             PG8_WAIT_V(8); PG8_WAIT_L(0); PG8_BAR; PG8_MMA(1, 0, At, B0); PG8_MMA(1, 1, At, B1); PG8_BAR; PG8_SCHED;
	s_setprio 1
	s_waitcnt lgkmcnt(0)
	v_mfma_f32_16x16x32_bf16 v[126:129], v[140:143], v[198:201], v[126:129]
	v_mfma_f32_16x16x32_bf16 v[118:121], v[160:163], v[198:201], v[118:121]
	v_mfma_f32_16x16x32_bf16 v[110:113], v[140:143], v[206:209], v[110:113]
	v_mfma_f32_16x16x32_bf16 v[102:105], v[160:163], v[206:209], v[102:105]
	v_mfma_f32_16x16x32_bf16 v[94:97], v[140:143], v[234:237], v[94:97]
	v_mfma_f32_16x16x32_bf16 v[86:89], v[160:163], v[234:237], v[86:89]
	v_mfma_f32_16x16x32_bf16 v[78:81], v[140:143], v[242:245], v[78:81]
	v_mfma_f32_16x16x32_bf16 v[70:73], v[160:163], v[242:245], v[70:73]
	v_mfma_f32_16x16x32_bf16 v[126:129], v[144:147], v[202:205], v[126:129]
	v_mfma_f32_16x16x32_bf16 v[118:121], v[164:167], v[202:205], v[118:121]
	v_mfma_f32_16x16x32_bf16 v[110:113], v[144:147], v[210:213], v[110:113]
	v_mfma_f32_16x16x32_bf16 v[102:105], v[164:167], v[210:213], v[102:105]
	v_mfma_f32_16x16x32_bf16 v[94:97], v[144:147], v[238:241], v[94:97]
	v_mfma_f32_16x16x32_bf16 v[86:89], v[164:167], v[238:241], v[86:89]
	v_mfma_f32_16x16x32_bf16 v[78:81], v[144:147], v[246:249], v[78:81]
	v_mfma_f32_16x16x32_bf16 v[70:73], v[164:167], v[246:249], v[70:73]
	s_setprio 0
	s_setprio 1
	v_mfma_f32_16x16x32_bf16 v[122:125], v[168:171], v[198:201], v[122:125]
	v_mfma_f32_16x16x32_bf16 v[114:117], v[176:179], v[198:201], v[114:117]
	v_mfma_f32_16x16x32_bf16 v[106:109], v[168:171], v[206:209], v[106:109]
	v_mfma_f32_16x16x32_bf16 v[98:101], v[176:179], v[206:209], v[98:101]
	v_mfma_f32_16x16x32_bf16 v[90:93], v[168:171], v[234:237], v[90:93]
	v_mfma_f32_16x16x32_bf16 v[82:85], v[176:179], v[234:237], v[82:85]
	v_mfma_f32_16x16x32_bf16 v[74:77], v[168:171], v[242:245], v[74:77]
	v_mfma_f32_16x16x32_bf16 v[66:69], v[176:179], v[242:245], v[66:69]
	v_mfma_f32_16x16x32_bf16 v[122:125], v[172:175], v[202:205], v[122:125]
	v_mfma_f32_16x16x32_bf16 v[114:117], v[194:197], v[202:205], v[114:117]
	v_mfma_f32_16x16x32_bf16 v[106:109], v[172:175], v[210:213], v[106:109]
	v_mfma_f32_16x16x32_bf16 v[98:101], v[194:197], v[210:213], v[98:101]
	v_mfma_f32_16x16x32_bf16 v[90:93], v[172:175], v[238:241], v[90:93]
	v_mfma_f32_16x16x32_bf16 v[82:85], v[194:197], v[238:241], v[82:85]
	v_mfma_f32_16x16x32_bf16 v[74:77], v[172:175], v[246:249], v[74:77]
	v_mfma_f32_16x16x32_bf16 v[66:69], v[194:197], v[246:249], v[66:69]
	s_setprio 0
	s_barrier
	s_add_i32 s58, s58, s26
	s_mov_b32 m0, s58
	ds_read_b128 v[198:201], v159 offset:16384
	ds_read_b128 v[202:205], v159 offset:17408
	ds_read_b128 v[206:209], v159 offset:18432
	ds_read_b128 v[210:213], v159 offset:19456
	ds_read_b128 v[234:237], v159 offset:20480
	ds_read_b128 v[238:241], v159 offset:21504
	ds_read_b128 v[242:245], v159 offset:22528
	ds_read_b128 v[246:249], v159 offset:23552
	global_load_lds_dwordx4 v0, s[6:7]
	s_add_i32 m0, s58, 0x2000
	s_add_u32 s58, s6, 0x80000
	s_addc_u32 s59, s7, 0
	s_add_i32 s75, s75, s26
	global_load_lds_dwordx4 v130, s[6:7]
	s_mov_b32 m0, s75
	s_nop 0
	global_load_lds_dwordx4 v0, s[58:59]
	s_add_i32 m0, s75, 0x2000
	s_nop 0
	global_load_lds_dwordx4 v130, s[58:59]
	s_mov_b32 m0, s27
	s_nop 0
	global_load_lds_dwordx4 v134, s[22:23]
	s_mov_b32 m0, s28
	s_nop 0
	global_load_lds_dwordx4 v132, s[22:23]
	s_waitcnt vmcnt(8)
	s_waitcnt lgkmcnt(0)
	s_barrier
	s_setprio 1
	s_waitcnt lgkmcnt(0)
	v_mfma_f32_16x16x32_bf16 v[62:65], v[140:143], v[198:201], v[62:65]
	v_mfma_f32_16x16x32_bf16 v[54:57], v[160:163], v[198:201], v[54:57]
	v_mfma_f32_16x16x32_bf16 v[46:49], v[140:143], v[206:209], v[46:49]
	v_mfma_f32_16x16x32_bf16 v[38:41], v[160:163], v[206:209], v[38:41]
	v_mfma_f32_16x16x32_bf16 v[30:33], v[140:143], v[234:237], v[30:33]
	v_mfma_f32_16x16x32_bf16 v[22:25], v[160:163], v[234:237], v[22:25]
	v_mfma_f32_16x16x32_bf16 v[14:17], v[140:143], v[242:245], v[14:17]
	v_mfma_f32_16x16x32_bf16 v[6:9], v[160:163], v[242:245], v[6:9]
	v_mfma_f32_16x16x32_bf16 v[62:65], v[144:147], v[202:205], v[62:65]
	v_mfma_f32_16x16x32_bf16 v[54:57], v[164:167], v[202:205], v[54:57]
	v_mfma_f32_16x16x32_bf16 v[46:49], v[144:147], v[210:213], v[46:49]
	v_mfma_f32_16x16x32_bf16 v[38:41], v[164:167], v[210:213], v[38:41]
	v_mfma_f32_16x16x32_bf16 v[30:33], v[144:147], v[238:241], v[30:33]
	v_mfma_f32_16x16x32_bf16 v[22:25], v[164:167], v[238:241], v[22:25]
	v_mfma_f32_16x16x32_bf16 v[14:17], v[144:147], v[246:249], v[14:17]
	v_mfma_f32_16x16x32_bf16 v[6:9], v[164:167], v[246:249], v[6:9]
	s_setprio 0
	s_setprio 1
	v_mfma_f32_16x16x32_bf16 v[58:61], v[168:171], v[198:201], v[58:61]
	v_mfma_f32_16x16x32_bf16 v[50:53], v[176:179], v[198:201], v[50:53]
	v_mfma_f32_16x16x32_bf16 v[42:45], v[168:171], v[206:209], v[42:45]
	v_mfma_f32_16x16x32_bf16 v[34:37], v[176:179], v[206:209], v[34:37]
	v_mfma_f32_16x16x32_bf16 v[26:29], v[168:171], v[234:237], v[26:29]
	v_mfma_f32_16x16x32_bf16 v[18:21], v[176:179], v[234:237], v[18:21]
	v_mfma_f32_16x16x32_bf16 v[10:13], v[168:171], v[242:245], v[10:13]
	v_mfma_f32_16x16x32_bf16 v[2:5], v[176:179], v[242:245], v[2:5]
	v_mfma_f32_16x16x32_bf16 v[58:61], v[172:175], v[202:205], v[58:61]
	v_mfma_f32_16x16x32_bf16 v[50:53], v[194:197], v[202:205], v[50:53]
	v_mfma_f32_16x16x32_bf16 v[42:45], v[172:175], v[210:213], v[42:45]
	v_mfma_f32_16x16x32_bf16 v[34:37], v[194:197], v[210:213], v[34:37]
	v_mfma_f32_16x16x32_bf16 v[26:29], v[172:175], v[238:241], v[26:29]
	v_mfma_f32_16x16x32_bf16 v[18:21], v[194:197], v[238:241], v[18:21]
	v_mfma_f32_16x16x32_bf16 v[10:13], v[172:175], v[246:249], v[10:13]
	v_mfma_f32_16x16x32_bf16 v[2:5], v[194:197], v[246:249], v[2:5]
	s_setprio 0
	s_barrier
; #define PG8_STAGE(bufoff, gbase, voff) do { _Pragma("unroll") for (int _i = 0; _i < 2; ++_i) \
;         __builtin_amdgcn_global_load_lds((const unsigned*)((const char*)(gbase) + (voff)[_i]), (LAS unsigned*)(lds + (bufoff) + ldsw + _i * 8192), 16, 0, 0); } while (0)
; #define PG8_LDA(dst, b, h) do { _Pragma("unroll") for (int m = 0; m < 4; ++m) _Pragma("unroll") for (int k = 0; k < 2; ++k) dst[m][k] = *(const LAS bf16x8*)(lds + PG8_SA(b, h) + aoff + m * 2048 + k * 1024); } while (0)
; #define PG8_LDB(dst, b, h) do { _Pragma("unroll") for (int n = 0; n < 2; ++n) _Pragma("unroll") for (int k = 0; k < 2; ++k) dst[n][k] = *(const LAS bf16x8*)(lds + PG8_SB(b, h) + boff + n * 2048 + k * 1024); } while (0)
; #define PG8_MMA(ai, bj, At, Bt) do { __builtin_amdgcn_s_setprio(1); _Pragma("unroll") for (int m = 0; m < 4; ++m) _Pragma("unroll") for (int n = 0; n < 2; ++n) _Pragma("unroll") for (int k = 0; k < 2; ++k) \
;         acc[ai][bj][m][n] = __builtin_amdgcn_mfma_f32_16x16x32_bf16(Bt[n][k], At[m][k], acc[ai][bj][m][n], 0, 0, 0); __builtin_amdgcn_s_setprio(0); } while (0)
; #define PG8_WAIT_V(n) asm volatile("s_waitcnt vmcnt(" #n ")" ::: "memory")
; #define PG8_WAIT_L(n) asm volatile("s_waitcnt lgkmcnt(" #n ")" ::: "memory")
; #define PG8_BAR __builtin_amdgcn_s_barrier()
; #define PG8_SCHED __builtin_amdgcn_sched_barrier(0)
; template <class Epi, class Sched, bool ALIGN_EPI = true, bool SP2 = true>
; __device__ __forceinline__ void gemm_phase(LAS unsigned char* lds, const Gemm g, const Sched& S, const Epi& E) {
;     ...
;             PG8_LDB(B0, 1, 0); PG8_LDB(B1, 1, 1); PG8_SCHED; PG8_LDA(At, 1, 0); PG8_STAGE(PG8_SA(0, 1), a2 + hstep, voffA);
;             PG8_WAIT_V(8); PG8_WAIT_L(0); PG8_BAR; PG8_MMA(0, 0, At, B0); PG8_MMA(0, 1, At, B1); PG8_BAR; PG8_SCHED;
;             PG8_LDA(At, 1, 1); PG8_STAGE(PG8_SB(1, 0), b3, voffB); PG8_STAGE(PG8_SB(1, 1), b3 + hstep, voffB); PG8_STAGE(PG8_SA(1, 0), a3, voffA);
;             PG8_WAIT_V(8); PG8_WAIT_L(0); PG8_BAR; PG8_MMA(1, 0, At, B0); PG8_MMA(1, 1, At, B1); PG8_BAR; PG8_SCHED;
;     ...
;         if constexpr (ALIGN_EPI) { if (wr == 0) PG8_BAR; }
	s_add_i32 s58, 0, 0x18000
	v_add_u32_e32 v150, s58, v153
	s_add_i32 s59, 0, 0x1c000
	ds_read_b128 v[140:143], v150
	ds_read_b128 v[144:147], v150 offset:1024
	ds_read_b128 v[160:163], v150 offset:2048
	ds_read_b128 v[164:167], v150 offset:3072
	ds_read_b128 v[168:171], v150 offset:16384
	ds_read_b128 v[172:175], v150 offset:17408
	ds_read_b128 v[176:179], v150 offset:18432
	ds_read_b128 v[194:197], v150 offset:19456
	s_add_u32 s22, s22, 0x80000
	s_addc_u32 s23, s23, 0
	s_mov_b32 m0, s29
	ds_read_b128 v[198:201], v159 offset:32768
	ds_read_b128 v[202:205], v159 offset:33792
	ds_read_b128 v[206:209], v159 offset:34816
	ds_read_b128 v[210:213], v159 offset:35840
	ds_read_b128 v[234:237], v159 offset:36864
	ds_read_b128 v[238:241], v159 offset:37888
	ds_read_b128 v[242:245], v159 offset:38912
	ds_read_b128 v[246:249], v159 offset:39936
	global_load_lds_dwordx4 v134, s[22:23]
	s_mov_b32 m0, s30
	s_nop 0
	global_load_lds_dwordx4 v132, s[22:23]
	s_waitcnt vmcnt(8)
	s_waitcnt lgkmcnt(0)
	s_barrier
	s_setprio 1
	s_waitcnt lgkmcnt(0)
	v_mfma_f32_16x16x32_bf16 v[126:129], v[140:143], v[198:201], v[126:129]
	v_mfma_f32_16x16x32_bf16 v[118:121], v[160:163], v[198:201], v[118:121]
	v_mfma_f32_16x16x32_bf16 v[110:113], v[140:143], v[206:209], v[110:113]
	v_mfma_f32_16x16x32_bf16 v[102:105], v[160:163], v[206:209], v[102:105]
	v_mfma_f32_16x16x32_bf16 v[94:97], v[140:143], v[234:237], v[94:97]
	v_mfma_f32_16x16x32_bf16 v[86:89], v[160:163], v[234:237], v[86:89]
	v_mfma_f32_16x16x32_bf16 v[78:81], v[140:143], v[242:245], v[78:81]
	v_mfma_f32_16x16x32_bf16 v[70:73], v[160:163], v[242:245], v[70:73]
	v_mfma_f32_16x16x32_bf16 v[126:129], v[144:147], v[202:205], v[126:129]
	v_mfma_f32_16x16x32_bf16 v[118:121], v[164:167], v[202:205], v[118:121]
	v_mfma_f32_16x16x32_bf16 v[110:113], v[144:147], v[210:213], v[110:113]
	v_mfma_f32_16x16x32_bf16 v[102:105], v[164:167], v[210:213], v[102:105]
	v_mfma_f32_16x16x32_bf16 v[94:97], v[144:147], v[238:241], v[94:97]
	v_mfma_f32_16x16x32_bf16 v[86:89], v[164:167], v[238:241], v[86:89]
	v_mfma_f32_16x16x32_bf16 v[78:81], v[144:147], v[246:249], v[78:81]
	v_mfma_f32_16x16x32_bf16 v[70:73], v[164:167], v[246:249], v[70:73]
	s_setprio 0
	s_setprio 1
	v_mfma_f32_16x16x32_bf16 v[122:125], v[168:171], v[198:201], v[122:125]
	v_mfma_f32_16x16x32_bf16 v[114:117], v[176:179], v[198:201], v[114:117]
	v_mfma_f32_16x16x32_bf16 v[106:109], v[168:171], v[206:209], v[106:109]
	v_mfma_f32_16x16x32_bf16 v[98:101], v[176:179], v[206:209], v[98:101]
	v_mfma_f32_16x16x32_bf16 v[90:93], v[168:171], v[234:237], v[90:93]
	v_mfma_f32_16x16x32_bf16 v[82:85], v[176:179], v[234:237], v[82:85]
	v_mfma_f32_16x16x32_bf16 v[74:77], v[168:171], v[242:245], v[74:77]
	v_mfma_f32_16x16x32_bf16 v[66:69], v[176:179], v[242:245], v[66:69]
	v_mfma_f32_16x16x32_bf16 v[122:125], v[172:175], v[202:205], v[122:125]
	v_mfma_f32_16x16x32_bf16 v[114:117], v[194:197], v[202:205], v[114:117]
	v_mfma_f32_16x16x32_bf16 v[106:109], v[172:175], v[210:213], v[106:109]
	v_mfma_f32_16x16x32_bf16 v[98:101], v[194:197], v[210:213], v[98:101]
	v_mfma_f32_16x16x32_bf16 v[90:93], v[172:175], v[238:241], v[90:93]
	v_mfma_f32_16x16x32_bf16 v[82:85], v[194:197], v[238:241], v[82:85]
	v_mfma_f32_16x16x32_bf16 v[74:77], v[172:175], v[246:249], v[74:77]
	v_mfma_f32_16x16x32_bf16 v[66:69], v[194:197], v[246:249], v[66:69]
	s_setprio 0
	s_barrier
	s_add_i32 s32, s58, s26
	s_add_u32 s6, s6, s92
	s_addc_u32 s7, s7, s93
	s_mov_b32 m0, s32
	ds_read_b128 v[198:201], v159 offset:49152
	ds_read_b128 v[202:205], v159 offset:50176
	ds_read_b128 v[206:209], v159 offset:51200
	ds_read_b128 v[210:213], v159 offset:52224
	ds_read_b128 v[234:237], v159 offset:53248
	ds_read_b128 v[238:241], v159 offset:54272
	ds_read_b128 v[242:245], v159 offset:55296
	ds_read_b128 v[246:249], v159 offset:56320
	global_load_lds_dwordx4 v0, s[6:7]
	s_add_i32 m0, s32, 0x2000
	s_add_i32 s32, s59, s26
	global_load_lds_dwordx4 v130, s[6:7]
	s_add_u32 s6, s6, 0x80000
	s_addc_u32 s7, s7, 0
	s_mov_b32 m0, s32
	s_nop 0
	global_load_lds_dwordx4 v0, s[6:7]
	s_add_i32 m0, s32, 0x2000
	s_nop 0
	global_load_lds_dwordx4 v130, s[6:7]
	s_add_u32 s22, s22, 0xfff80080
	s_addc_u32 s23, s23, -1
	s_mov_b32 m0, s31
	s_nop 0
	global_load_lds_dwordx4 v134, s[22:23]
	s_mov_b32 m0, s34
	s_nop 0
	global_load_lds_dwordx4 v132, s[22:23]
	s_waitcnt vmcnt(8)
	s_waitcnt lgkmcnt(0)
	s_barrier
	s_setprio 1
	s_waitcnt lgkmcnt(0)
	v_mfma_f32_16x16x32_bf16 v[62:65], v[140:143], v[198:201], v[62:65]
	v_mfma_f32_16x16x32_bf16 v[54:57], v[160:163], v[198:201], v[54:57]
	v_mfma_f32_16x16x32_bf16 v[46:49], v[140:143], v[206:209], v[46:49]
	v_mfma_f32_16x16x32_bf16 v[38:41], v[160:163], v[206:209], v[38:41]
	v_mfma_f32_16x16x32_bf16 v[30:33], v[140:143], v[234:237], v[30:33]
	v_mfma_f32_16x16x32_bf16 v[22:25], v[160:163], v[234:237], v[22:25]
	v_mfma_f32_16x16x32_bf16 v[14:17], v[140:143], v[242:245], v[14:17]
	v_mfma_f32_16x16x32_bf16 v[6:9], v[160:163], v[242:245], v[6:9]
	v_mfma_f32_16x16x32_bf16 v[62:65], v[144:147], v[202:205], v[62:65]
	v_mfma_f32_16x16x32_bf16 v[54:57], v[164:167], v[202:205], v[54:57]
	v_mfma_f32_16x16x32_bf16 v[46:49], v[144:147], v[210:213], v[46:49]
	v_mfma_f32_16x16x32_bf16 v[38:41], v[164:167], v[210:213], v[38:41]
	v_mfma_f32_16x16x32_bf16 v[30:33], v[144:147], v[238:241], v[30:33]
	v_mfma_f32_16x16x32_bf16 v[22:25], v[164:167], v[238:241], v[22:25]
	v_mfma_f32_16x16x32_bf16 v[14:17], v[144:147], v[246:249], v[14:17]
	v_mfma_f32_16x16x32_bf16 v[6:9], v[164:167], v[246:249], v[6:9]
	s_setprio 0
	s_setprio 1
	v_mfma_f32_16x16x32_bf16 v[58:61], v[168:171], v[198:201], v[58:61]
	v_mfma_f32_16x16x32_bf16 v[50:53], v[176:179], v[198:201], v[50:53]
	v_mfma_f32_16x16x32_bf16 v[42:45], v[168:171], v[206:209], v[42:45]
	v_mfma_f32_16x16x32_bf16 v[34:37], v[176:179], v[206:209], v[34:37]
	v_mfma_f32_16x16x32_bf16 v[26:29], v[168:171], v[234:237], v[26:29]
	v_mfma_f32_16x16x32_bf16 v[18:21], v[176:179], v[234:237], v[18:21]
	v_mfma_f32_16x16x32_bf16 v[10:13], v[168:171], v[242:245], v[10:13]
	v_mfma_f32_16x16x32_bf16 v[2:5], v[176:179], v[242:245], v[2:5]
	v_mfma_f32_16x16x32_bf16 v[58:61], v[172:175], v[202:205], v[58:61]
	v_mfma_f32_16x16x32_bf16 v[50:53], v[194:197], v[202:205], v[50:53]
	v_mfma_f32_16x16x32_bf16 v[42:45], v[172:175], v[210:213], v[42:45]
	v_mfma_f32_16x16x32_bf16 v[34:37], v[194:197], v[210:213], v[34:37]
	v_mfma_f32_16x16x32_bf16 v[26:29], v[172:175], v[238:241], v[26:29]
	v_mfma_f32_16x16x32_bf16 v[18:21], v[194:197], v[238:241], v[18:21]
	v_mfma_f32_16x16x32_bf16 v[10:13], v[172:175], v[246:249], v[10:13]
	v_mfma_f32_16x16x32_bf16 v[2:5], v[194:197], v[246:249], v[2:5]
	s_setprio 0
	s_barrier
	s_add_i32 s74, s74, 2
	s_add_u32 s4, s4, 0x100
	s_addc_u32 s5, s5, 0
	s_add_u32 s72, s72, 0x100
	s_addc_u32 s73, s73, 0
	s_cmp_gt_u32 s74, 29
	s_cbranch_scc0 .LBB0_871
	s_and_b64 vcc, exec, s[12:13]
	s_cbranch_vccz .LBB0_874
	s_barrier
